# speedup vs baseline: 1.0078x; 1.0078x over previous
; __device__ void phase5(const Params& p) {
;   char* ws = p.ws;
;   const u16* mi = (const u16*)(ws + OFF_XA);
;   u16* o = (u16*)(ws + OFF_ZA);
;   float* sso = (float*)(ws + OFF_SSO);
;   constexpr int nM = T / 256, nN = D / 256;
;   f32x4 acc[2][2][4][2];
;   for (int it = 0;; ++it) {
;     int pm, pn;
;     if (!tile_coords(it, nM, nN, pm, pn)) break;
;     const int to = pm * 256, fo = pn * 256;
.LBB0_650:
	s_or_b64 exec, exec, s[0:1]
	s_add_u32 s14, s30, 0x28000
	s_addc_u32 s15, s31, 0
	s_add_u32 s3, s30, 0x3500000
	s_addc_u32 s66, s31, 0
	s_add_u32 s67, s30, 0x3500f80
	s_addc_u32 s70, s31, 0
	s_mov_b32 s71, 0
	s_mov_b32 s100, 0
	v_mov_b32_e32 v129, 0
	s_mov_b32 s72, 0x10000
	s_mov_b32 s73, 0x14000
	s_mov_b64 s[0:1], 0x80
	s_mov_b32 s76, 0x18000
	s_mov_b32 s77, 0x1c000
	s_mov_b64 s[6:7], 0x3580080
	s_mov_b64 s[8:9], 0x8000100
	s_mov_b64 s[16:17], 0x3500100
	s_mov_b64 s[18:19], 0x8080100
	s_mov_b64 s[20:21], 0x3580100
	s_mov_b64 s[22:23], 0x8000180
	s_mov_b64 s[44:45], 0x3500180
	s_mov_b64 s[46:47], 0x8080180
	s_movk_i32 s78, 0x100
	s_movk_i32 s79, 0x60
	v_mov_b32_e32 v141, 1
	v_mbcnt_hi_u32_b32 v140, -1, v195
	s_barrier
	s_branch .LBB0_653

; __device__ __forceinline__ int otid() { int t = threadIdx.x; asm volatile("" : "+v"(t)); return t; }
; #define WAIT_V(n) asm volatile("s_waitcnt vmcnt(" #n ")" ::: "memory")
; #define BAR __builtin_amdgcn_s_barrier()
; __device__ __forceinline__ void gemm_tile(const u16* __restrict__ A, const u16* __restrict__ Bt, const int K,
;                                           const int brow, const int bcol, f32x4 (&acc)[2][2][4][2],
;                                           const bool ZERO_INIT = true) {
;     ...
;   const int tidx = otid();
;   const int wid = tidx >> 6, lane = tidx & 63, wr = wid >> 2, wc = wid & 3, fr = lane & 15, fq = lane >> 4;
;   #pragma unroll
;   for (int a = 0; a < 2; ++a)
;     #pragma unroll
;     for (int b = 0; b < 2; ++b)
;       #pragma unroll
;       for (int m = 0; m < 4; ++m)
;         #pragma unroll
;         for (int n = 0; n < 2; ++n)
;           if (ZERO_INIT) acc[a][b][m][n] = f32x4{0.f, 0.f, 0.f, 0.f};
;   bf16x8 At[4][2], B0[2][2], B1[2][2];
;   const int nt = K / BK;
;   const unsigned ldsw = (unsigned)__builtin_amdgcn_readfirstlane(wid) * 1024u;
;   unsigned vo0, vo1;
;   {
;     int r0, c0, r1, c1;
;     stage_rc(tidx * 16, r0, c0);
;     stage_rc(tidx * 16 + 8192, r1, c1);
;     vo0 = (unsigned)(r0 * K + c0) * 2u;
;     vo1 = (unsigned)(r1 * K + c1) * 2u;
;   }
;   STAGE(SB(0, 0), Bt, bcol, 0); STAGE(SA(0, 0), A, brow, 0);
;   STAGE(SB(0, 1), Bt, bcol + HALF, 0); STAGE(SA(0, 1), A, brow + HALF, 0);
;   if (wr == 1) BAR;
;   WAIT_V(4); BAR;
;   STAGE(SB(1, 0), Bt, bcol, 1); STAGE(SA(1, 0), A, brow, 1); STAGE(SB(1, 1), Bt, bcol + HALF, 1);
.LBB0_656:
	s_mul_i32 s25, s71, s33
	s_add_i32 s24, s24, s25
	s_cmpk_gt_i32 s24, 0x4ff
	s_mov_b64 s[48:49], -1
	s_cbranch_scc1 .LBB0_652
	v_mov_b32_e32 v142, v194
	v_mov_b32_e32 v143, v194
	s_ashr_i32 s25, s24, 31
	v_bfe_i32 v2, v143, 27, 1
	v_lshlrev_b32_e32 v5, 4, v143
	v_lshrrev_b32_e32 v2, 22, v2
	v_add_u32_e32 v2, v5, v2
	v_and_b32_e32 v2, 0xfffffc00, v2
	v_sub_u32_e32 v2, v5, v2
	s_lshr_b32 s25, s25, 26
	v_lshrrev_b32_e32 v3, 4, v2
	s_add_i32 s25, s24, s25
	v_bitop3_b32 v4, v3, v2, 32 bitop3:0x6c
	v_ashrrev_i32_e32 v2, 31, v2
	s_and_b32 s48, s25, 0xffc0
	v_lshrrev_b32_e32 v2, 26, v2
	s_sub_i32 s24, s24, s48
	v_add_u32_e32 v2, v4, v2
	s_bfe_i32 s48, s24, 0x80000
	v_ashrrev_i32_e32 v2, 6, v2
	s_bfe_u32 s48, s48, 0x3000c
	v_mul_i32_i24_e32 v6, 64, v2
	s_add_i32 s48, s24, s48
	v_sub_u32_e32 v4, v4, v6
	v_add_u32_e32 v6, 0x2000, v5
	s_bfe_i32 s49, s48, 0x80000
	s_and_b32 s48, s48, 0xf8
	v_ashrrev_i32_e32 v5, 31, v6
	s_sub_i32 s24, s24, s48
	v_lshrrev_b32_e32 v5, 22, v5
	s_sext_i32_i8 s24, s24
	s_lshl_b32 s25, s25, 5
	v_add_u32_e32 v5, v6, v5
	s_sext_i32_i16 s49, s49
	s_and_b32 s25, s25, 0xfffff800
	s_lshl_b32 s24, s24, 8
	v_ashrrev_i32_e32 v5, 10, v5
	s_add_i32 s50, s24, s25
	s_lshl_b32 s24, s49, 5
	s_waitcnt lgkmcnt(0)
	v_ashrrev_i32_e32 v1, 6, v143
	v_mul_i32_i24_e32 v7, 0x400, v5
	s_and_b32 s48, s24, 0xffffff00
	v_readfirstlane_b32 s24, v1
	v_ashrrev_i32_e32 v0, 31, v143
	v_sub_u32_e32 v6, v6, v7
	s_ashr_i32 s51, s50, 31
	s_lshl_b32 s80, s24, 10
	v_lshrrev_b32_e32 v0, 26, v0
	v_lshrrev_b32_e32 v7, 4, v6
	s_lshl_b64 s[54:55], s[50:51], 12
	v_add_u32_e32 v0, v143, v0
	v_bitop3_b32 v8, v7, v6, 32 bitop3:0x6c
	v_lshlrev_b32_e32 v6, 3, v5
	s_add_u32 s58, s42, s54
	v_ashrrev_i32_e32 v0, 6, v0
	v_and_b32_e32 v7, 0xffff0, v6
	v_ashrrev_i32_e32 v6, 31, v8
	s_addc_u32 s59, s43, s55
	s_ashr_i32 s49, s48, 31
	v_lshlrev_b32_e32 v3, 3, v0
	v_lshrrev_b32_e32 v6, 26, v6
	s_add_i32 s51, s80, 0x10000
	s_add_i32 s81, s80, 0x12000
	s_lshl_b64 s[56:57], s[48:49], 12
	v_and_b32_e32 v3, 0xffff0, v3
	v_add_u32_e32 v10, v8, v6
	s_add_u32 s60, s3, s56
	v_add_u32_e32 v9, v2, v3
	v_lshlrev_b32_e32 v3, 5, v0
	v_ashrrev_i32_e32 v6, 6, v10
	v_and_b32_e32 v10, 0xc0, v10
	s_addc_u32 s61, s66, s57
	s_or_b32 s24, s50, 0x80
	v_and_b32_e32 v3, 32, v3
	v_ashrrev_i16_sdwa v4, v141, sext(v4) dst_sel:DWORD dst_unused:UNUSED_PAD src0_sel:DWORD src1_sel:BYTE_0
	v_add_u32_e32 v11, v6, v7
	v_lshlrev_b32_e32 v7, 5, v5
	v_sub_u32_e32 v8, v8, v10
	s_ashr_i32 s25, s24, 31
	v_bfe_i32 v4, v4, 0, 16
	v_and_b32_e32 v7, 32, v7
	v_ashrrev_i16_sdwa v8, v141, sext(v8) dst_sel:DWORD dst_unused:UNUSED_PAD src0_sel:DWORD src1_sel:BYTE_0
	v_lshl_or_b32 v9, v9, 11, v3
	s_add_i32 s49, s80, 0x2000
	s_lshl_b64 s[24:25], s[24:25], 12
	v_bfe_i32 v8, v8, 0, 16
	v_add_lshl_u32 v128, v9, v4, 1
	v_lshl_or_b32 v9, v11, 11, v7
	s_add_u32 s62, s42, s24
	s_addc_u32 s63, s43, s25
	v_add_lshl_u32 v130, v9, v8, 1
	s_or_b32 s24, s48, 0x80
	s_ashr_i32 s25, s24, 31
	s_add_i32 s82, s80, 0x14000
	s_add_i32 s83, s80, 0x16000
	s_lshl_b64 s[52:53], s[24:25], 12
	s_add_u32 s64, s3, s52
	s_addc_u32 s65, s66, s53
	s_add_i32 s24, s80, 0x4000
	s_add_i32 s25, s80, 0x6000
	v_ashrrev_i32_e32 v9, 8, v143
	v_mov_b32_e32 v250, v128
	v_mov_b32_e32 v251, v130
	s_cmp_eq_u32 s100, 1
	s_cbranch_scc1 .Lp5_pf_skip
	s_mov_b32 m0, s51
	s_nop 0
	global_load_lds_dwordx4 v128, s[58:59]
	s_mov_b32 m0, s81
	s_nop 0
	global_load_lds_dwordx4 v130, s[58:59]
	s_mov_b32 m0, s80
	s_nop 0
	global_load_lds_dwordx4 v128, s[60:61]
	s_mov_b32 m0, s49
	s_nop 0
	global_load_lds_dwordx4 v130, s[60:61]
	s_mov_b32 m0, s82
	s_nop 0
	global_load_lds_dwordx4 v128, s[62:63]
	s_mov_b32 m0, s83
	s_nop 0
	global_load_lds_dwordx4 v130, s[62:63]
	s_mov_b32 m0, s24
	s_nop 0
	global_load_lds_dwordx4 v128, s[64:65]
	s_mov_b32 m0, s25
	s_nop 0
	global_load_lds_dwordx4 v130, s[64:65]
.Lp5_pf_skip:
	v_cmp_eq_u32_e32 vcc, 1, v9
	s_and_saveexec_b64 s[64:65], vcc
	s_cbranch_execz .LBB0_659
	s_barrier
.LBB0_659:
	s_or_b64 exec, exec, s[64:65]
	v_mov_b32_e32 v131, v129
	v_lshl_add_u64 v[10:11], s[58:59], 0, v[128:129]
	v_lshl_add_u64 v[12:13], s[58:59], 0, v[130:131]
	s_add_i32 s58, s80, 0x18000
	v_lshl_add_u64 v[10:11], v[10:11], 0, s[0:1]
	s_mov_b32 m0, s58
	s_add_i32 s59, s80, 0x1a000
	v_lshl_add_u64 v[14:15], s[60:61], 0, v[128:129]
	v_lshl_add_u64 v[16:17], s[60:61], 0, v[130:131]
	s_cmp_eq_u32 s100, 1
	s_cbranch_scc1 .Lp5_w1_pf
	s_waitcnt vmcnt(4)
	s_branch .Lp5_w1_done
.Lp5_w1_pf:
	s_waitcnt vmcnt(24)
; #define WAIT_V(n) asm volatile("s_waitcnt vmcnt(" #n ")" ::: "memory")
; #define BAR __builtin_amdgcn_s_barrier()
; __device__ __forceinline__ void gemm_tile(const u16* __restrict__ A, const u16* __restrict__ Bt, const int K,
;                                           const int brow, const int bcol, f32x4 (&acc)[2][2][4][2],
;                                           const bool ZERO_INIT = true) {
;     ...
;   #pragma unroll
;   for (int a = 0; a < 2; ++a)
;     #pragma unroll
;     for (int b = 0; b < 2; ++b)
;       #pragma unroll
;       for (int m = 0; m < 4; ++m)
;         #pragma unroll
;         for (int n = 0; n < 2; ++n)
;           if (ZERO_INIT) acc[a][b][m][n] = f32x4{0.f, 0.f, 0.f, 0.f};
;   bf16x8 At[4][2], B0[2][2], B1[2][2];
;   const int nt = K / BK;
;   const unsigned ldsw = (unsigned)__builtin_amdgcn_readfirstlane(wid) * 1024u;
;   unsigned vo0, vo1;
;   {
;     int r0, c0, r1, c1;
;     stage_rc(tidx * 16, r0, c0);
;     stage_rc(tidx * 16 + 8192, r1, c1);
;     vo0 = (unsigned)(r0 * K + c0) * 2u;
;     vo1 = (unsigned)(r1 * K + c1) * 2u;
;   }
;   STAGE(SB(0, 0), Bt, bcol, 0); STAGE(SA(0, 0), A, brow, 0);
;   STAGE(SB(0, 1), Bt, bcol + HALF, 0); STAGE(SA(0, 1), A, brow + HALF, 0);
;   if (wr == 1) BAR;
;   WAIT_V(4); BAR;
;   STAGE(SB(1, 0), Bt, bcol, 1); STAGE(SA(1, 0), A, brow, 1); STAGE(SB(1, 1), Bt, bcol + HALF, 1);
;   WAIT_V(6); BAR;
.Lp5_w1_done:
	s_barrier
	global_load_lds_dwordx4 v[10:11], off
	v_lshl_add_u64 v[10:11], v[12:13], 0, s[0:1]
	s_mov_b32 m0, s59
	s_add_i32 s60, s80, 0x8000
	global_load_lds_dwordx4 v[10:11], off
	v_lshl_add_u64 v[10:11], v[14:15], 0, s[0:1]
	s_mov_b32 m0, s60
	s_add_i32 s61, s80, 0xa000
	v_lshl_add_u64 v[18:19], s[62:63], 0, v[128:129]
	v_lshl_add_u64 v[20:21], s[62:63], 0, v[130:131]
	global_load_lds_dwordx4 v[10:11], off
	v_lshl_add_u64 v[10:11], v[16:17], 0, s[0:1]
	s_mov_b32 m0, s61
	s_add_i32 s62, s80, 0x1c000
	global_load_lds_dwordx4 v[10:11], off
	v_lshl_add_u64 v[10:11], v[18:19], 0, s[0:1]
	s_mov_b32 m0, s62
	s_add_i32 s63, s80, 0x1e000
	global_load_lds_dwordx4 v[10:11], off
	v_lshl_add_u64 v[10:11], v[20:21], 0, s[0:1]
	s_mov_b32 m0, s63
	v_lshlrev_b32_e32 v0, 14, v0
	global_load_lds_dwordx4 v[10:11], off
	v_and_b32_e32 v22, 15, v143
	v_lshlrev_b32_e32 v1, 12, v1
	v_lshlrev_b32_e32 v12, 2, v143
	v_and_b32_e32 v0, 0x7fff8000, v0
	v_and_b32_e32 v23, 48, v143
	v_and_b32_e32 v10, 0x3000, v1
	v_lshlrev_b32_e32 v1, 6, v22
	v_and_b32_e32 v12, 32, v12
	v_lshl_add_u32 v0, v2, 11, v0
	v_lshlrev_b32_e32 v2, 14, v5
	v_or_b32_e32 v11, v1, v23
	v_bitop3_b32 v13, v1, v12, v23 bitop3:0x36
	v_lshlrev_b32_e32 v1, 6, v143
	v_and_b32_e32 v2, 0x7fff8000, v2
	v_and_b32_e32 v1, 0x3c0, v1
	v_or_b32_e32 v0, v0, v3
	v_lshl_add_u32 v2, v6, 11, v2
	s_cmp_eq_u32 s100, 1
	s_cbranch_scc1 .Lp5_w2_pf
	s_waitcnt vmcnt(6)
	s_branch .Lp5_w2_done
.Lp5_w2_pf:
	s_waitcnt vmcnt(26)
.Lp5_w2_done:
	v_bitop3_b32 v14, v11, s72, v12 bitop3:0xde
	v_bitop3_b32 v15, v11, s73, v12 bitop3:0xde
	v_bitop3_b32 v16, v11, s76, v12 bitop3:0xde
	v_bitop3_b32 v11, v11, s77, v12 bitop3:0xde
	v_lshlrev_b32_e32 v9, 13, v9
	v_bitop3_b32 v12, v1, v12, v23 bitop3:0x36
	v_add_lshl_u32 v0, v0, v4, 1
	v_mov_b32_e32 v1, v129
	v_or_b32_e32 v2, v2, v7
	v_or_b32_e32 v17, 0x800, v9
	v_or_b32_e32 v18, 0x1000, v9
	v_or_b32_e32 v19, 0x1800, v9
	v_lshl_add_u64 v[132:133], s[54:55], 0, v[0:1]
	v_add_lshl_u32 v2, v2, v8, 1
	v_mov_b32_e32 v3, v129
	v_lshl_add_u64 v[136:137], s[56:57], 0, v[0:1]
	v_mov_b32_e32 v0, 0
	v_lshl_add_u64 v[134:135], s[54:55], 0, v[2:3]
	v_lshl_add_u64 v[138:139], s[56:57], 0, v[2:3]
	s_mov_b32 s57, -2
	v_add_u32_e32 v151, v14, v10
	v_add_u32_e32 v147, v13, v9
	v_add_u32_e32 v146, v12, v17
	v_add_u32_e32 v145, v12, v18
	v_add_u32_e32 v144, v12, v19
	s_add_i32 s64, s80, 0xc000
	s_add_i32 s56, s80, 0xe000
	v_add_u32_e32 v150, v15, v10
	v_add_u32_e32 v149, v16, v10
	v_add_u32_e32 v148, v11, v10
	s_mov_b64 s[54:55], s[30:31]
	v_mov_b32_e32 v1, v0
	v_mov_b32_e32 v2, v0
	v_mov_b32_e32 v3, v0
	v_mov_b32_e32 v4, v0
	v_mov_b32_e32 v5, v0
	v_mov_b32_e32 v6, v0
	v_mov_b32_e32 v7, v0
	v_mov_b32_e32 v8, v0
	v_mov_b32_e32 v9, v0
	v_mov_b32_e32 v10, v0
	v_mov_b32_e32 v11, v0
	v_mov_b32_e32 v12, v0
	v_mov_b32_e32 v13, v0
	v_mov_b32_e32 v14, v0
	v_mov_b32_e32 v15, v0
	v_mov_b32_e32 v16, v0
	v_mov_b32_e32 v17, v0
	v_mov_b32_e32 v18, v0
	v_mov_b32_e32 v19, v0
	v_mov_b32_e32 v20, v0
	v_mov_b32_e32 v21, v0
	v_mov_b32_e32 v22, v0
	v_mov_b32_e32 v23, v0
	v_mov_b32_e32 v24, v0
	v_mov_b32_e32 v25, v0
	v_mov_b32_e32 v26, v0
	v_mov_b32_e32 v27, v0
	v_mov_b32_e32 v28, v0
	v_mov_b32_e32 v29, v0
	v_mov_b32_e32 v30, v0
	v_mov_b32_e32 v31, v0
	v_mov_b32_e32 v32, v0
	v_mov_b32_e32 v33, v0
	v_mov_b32_e32 v34, v0
	v_mov_b32_e32 v35, v0
	v_mov_b32_e32 v36, v0
	v_mov_b32_e32 v37, v0
	v_mov_b32_e32 v38, v0
	v_mov_b32_e32 v39, v0
	v_mov_b32_e32 v40, v0
	v_mov_b32_e32 v41, v0
	v_mov_b32_e32 v42, v0
	v_mov_b32_e32 v43, v0
	v_mov_b32_e32 v44, v0
	v_mov_b32_e32 v45, v0
	v_mov_b32_e32 v46, v0
	v_mov_b32_e32 v47, v0
	v_mov_b32_e32 v48, v0
	v_mov_b32_e32 v49, v0
	v_mov_b32_e32 v50, v0
	v_mov_b32_e32 v51, v0
	v_mov_b32_e32 v52, v0
	v_mov_b32_e32 v53, v0
	v_mov_b32_e32 v54, v0
	v_mov_b32_e32 v55, v0
	v_mov_b32_e32 v56, v0
	v_mov_b32_e32 v57, v0
	v_mov_b32_e32 v58, v0
	v_mov_b32_e32 v59, v0
	v_mov_b32_e32 v60, v0
	v_mov_b32_e32 v61, v0
	v_mov_b32_e32 v62, v0
	v_mov_b32_e32 v63, v0
	v_mov_b32_e32 v64, v0
	v_mov_b32_e32 v65, v0
	v_mov_b32_e32 v66, v0
	v_mov_b32_e32 v67, v0
	v_mov_b32_e32 v68, v0
	v_mov_b32_e32 v69, v0
	v_mov_b32_e32 v70, v0
	v_mov_b32_e32 v71, v0
	v_mov_b32_e32 v72, v0
	v_mov_b32_e32 v73, v0
	v_mov_b32_e32 v74, v0
	v_mov_b32_e32 v75, v0
	v_mov_b32_e32 v76, v0
	v_mov_b32_e32 v77, v0
	v_mov_b32_e32 v78, v0
	v_mov_b32_e32 v79, v0
	v_mov_b32_e32 v80, v0
	v_mov_b32_e32 v81, v0
	v_mov_b32_e32 v82, v0
	v_mov_b32_e32 v83, v0
	v_mov_b32_e32 v84, v0
	v_mov_b32_e32 v85, v0
	v_mov_b32_e32 v86, v0
	v_mov_b32_e32 v87, v0
	v_mov_b32_e32 v88, v0
	v_mov_b32_e32 v89, v0
	v_mov_b32_e32 v90, v0
	v_mov_b32_e32 v91, v0
	v_mov_b32_e32 v92, v0
	v_mov_b32_e32 v93, v0
	v_mov_b32_e32 v94, v0
	v_mov_b32_e32 v95, v0
	v_mov_b32_e32 v96, v0
	v_mov_b32_e32 v97, v0
	v_mov_b32_e32 v98, v0
	v_mov_b32_e32 v99, v0
	v_mov_b32_e32 v100, v0
	v_mov_b32_e32 v101, v0
	v_mov_b32_e32 v102, v0
	v_mov_b32_e32 v103, v0
	v_mov_b32_e32 v104, v0
	v_mov_b32_e32 v105, v0
	v_mov_b32_e32 v106, v0
	v_mov_b32_e32 v107, v0
	v_mov_b32_e32 v108, v0
	v_mov_b32_e32 v109, v0
	v_mov_b32_e32 v110, v0
	v_mov_b32_e32 v111, v0
	v_mov_b32_e32 v112, v0
	v_mov_b32_e32 v113, v0
	v_mov_b32_e32 v114, v0
	v_mov_b32_e32 v115, v0
	v_mov_b32_e32 v116, v0
	v_mov_b32_e32 v117, v0
	v_mov_b32_e32 v118, v0
	v_mov_b32_e32 v119, v0
	v_mov_b32_e32 v120, v0
	v_mov_b32_e32 v121, v0
	v_mov_b32_e32 v122, v0
	v_mov_b32_e32 v123, v0
	v_mov_b32_e32 v124, v0
	v_mov_b32_e32 v125, v0
	v_mov_b32_e32 v126, v0
	v_mov_b32_e32 v127, v0
	s_barrier

; __device__ __forceinline__ bool tile_coords(int it, int nM, int nN, int& pm, int& pn) {
;   const int G = gridDim.x, b = blockIdx.x, ntiles = nM * nN;
;   int L;
;   if ((G & 7) == 0 && (it + 1) * G <= ntiles) L = it * G + (b & 7) * (G >> 3) + (b >> 3);
;   else L = it * G + b;
;   if (L >= ntiles) return false;
;   const int nig = 8 * nN, gid = L / nig, fm = gid * 8, gsz = min(nM - fm, 8);
;   pm = fm + (L % nig) % gsz;
;   pn = (L % nig) / gsz;
;   return true;
; __device__ void phase5(const Params& p) {
;     ...
;     #pragma unroll
;     for (int bj = 0; bj < 2; ++bj)
;       #pragma unroll
;       for (int n = 0; n < 2; ++n) {
;         const int t = EPI_T(bj, n);
;         float part = 0.f;
;         #pragma unroll
;         for (int ai = 0; ai < 2; ++ai)
;           #pragma unroll
;           for (int m = 0; m < 4; ++m) {
;             const f32x4 v = acc[ai][bj][m][n];
;             part += v[0] * v[0] + v[1] * v[1] + v[2] * v[2] + v[3] * v[3];
;             v2u ov; ov.x = pk2(v[0], v[1]); ov.y = pk2(v[2], v[3]);
;             *reinterpret_cast<v2u*>(o + (size_t)t * D + EPI_F(ai, m)) = ov;
;           }
;         tok_ss_atomic(part, sso + t, fq);
;       }
.LBB0_663:
	s_or_b64 exec, exec, s[52:53]
	v_and_b32_e32 v130, 15, v194
	v_lshrrev_b32_e32 v131, 1, v194
	v_and_b32_e32 v131, 0x60, v131
	v_add3_u32 v132, s50, v130, v131
	v_bfe_u32 v134, v194, 4, 2
	v_lshrrev_b32_e32 v135, 2, v194
	v_and_b32_e32 v135, 0xffffffc0, v135
	v_cmp_eq_u32_e64 s[52:53], 0, v134
	s_add_i32 s24, s71, 1
	s_mul_i32 s25, s24, s33
	s_add_i32 s81, s25, s33
	s_mov_b32 s82, s2
	s_and_b32 s83, s33, 7
	s_cmp_lg_u32 s83, 0
	s_cbranch_scc1 .Lp5n_base
	s_cmpk_gt_i32 s81, 0x500
	s_cbranch_scc1 .Lp5n_base
	s_mov_b32 s82, s35
.Lp5n_base:
	s_add_i32 s24, s82, s25
	s_mov_b32 s100, 0
	s_cmpk_gt_i32 s24, 0x4ff
	s_cbranch_scc1 .Lp5n_done
	s_lshr_b32 s25, s24, 6
	s_and_b32 s56, s24, 7
	s_lshl_b32 s25, s25, 3
	s_add_i32 s25, s25, s56
	s_lshl_b32 s25, s25, 8
	s_bfe_u32 s56, s24, 0x30003
	s_lshl_b32 s56, s56, 8
	s_lshl_b32 s57, s25, 12
	s_add_u32 s62, s42, s57
	s_addc_u32 s63, s43, 0
	s_or_b32 s57, s25, 0x80
	s_lshl_b32 s57, s57, 12
	s_add_u32 s64, s42, s57
	s_addc_u32 s65, s43, 0
	s_lshl_b32 s57, s56, 12
	s_add_u32 s58, s3, s57
	s_addc_u32 s59, s66, 0
	s_or_b32 s57, s56, 0x80
	s_lshl_b32 s57, s57, 12
	s_add_u32 s60, s3, s57
	s_addc_u32 s61, s66, 0
	s_add_u32 m0, s80, 0x10000
	s_nop 0
	global_load_lds_dwordx4 v250, s[62:63]
	s_add_u32 m0, s80, 0x12000
	s_nop 0
	global_load_lds_dwordx4 v251, s[62:63]
	s_add_u32 m0, s80, 0x0
	s_nop 0
	global_load_lds_dwordx4 v250, s[58:59]
	s_add_u32 m0, s80, 0x2000
	s_nop 0
	global_load_lds_dwordx4 v251, s[58:59]
	s_add_u32 m0, s80, 0x14000
	s_nop 0
	global_load_lds_dwordx4 v250, s[64:65]
	s_add_u32 m0, s80, 0x16000
	s_nop 0
	global_load_lds_dwordx4 v251, s[64:65]
	s_add_u32 m0, s80, 0x4000
	s_nop 0
	global_load_lds_dwordx4 v250, s[60:61]
	s_add_u32 m0, s80, 0x6000
	s_nop 0
	global_load_lds_dwordx4 v251, s[60:61]
	s_mov_b32 s100, 1
.Lp5n_done:
	v_and_b32_e32 v136, 1, v134
	v_lshlrev_b32_e32 v137, 2, v134
	v_mad_u32_u24 v137, v136, 12, v137
	v_add3_u32 v137, v137, v135, s48
	v_lshl_add_u32 v137, v132, 11, v137
	v_lshlrev_b32_e32 v148, 1, v137
	v_add_u32_e32 v149, 0x10000, v148
	v_add_u32_e32 v150, 0x80000, v148
	v_add_u32_e32 v151, 0x90000, v148
	v_lshlrev_b32_e32 v152, 2, v132
	v_add_u32_e32 v153, 64, v152
	v_add_u32_e32 v154, 512, v152
	v_add_u32_e32 v155, 576, v152
	v_pk_mul_f32 v[160:161], v[124:125], v[124:125]
	v_pk_mul_f32 v[162:163], v[126:127], v[126:127]
	v_pk_fma_f32 v[160:161], v[116:117], v[116:117], v[160:161]
	v_pk_fma_f32 v[162:163], v[118:119], v[118:119], v[162:163]
	v_pk_fma_f32 v[160:161], v[112:113], v[112:113], v[160:161]
	v_pk_fma_f32 v[162:163], v[114:115], v[114:115], v[162:163]
	v_pk_fma_f32 v[160:161], v[108:109], v[108:109], v[160:161]
	v_pk_fma_f32 v[162:163], v[110:111], v[110:111], v[162:163]
	v_pk_fma_f32 v[160:161], v[120:121], v[120:121], v[160:161]
	v_pk_fma_f32 v[162:163], v[122:123], v[122:123], v[162:163]
	v_pk_fma_f32 v[160:161], v[96:97], v[96:97], v[160:161]
	v_pk_fma_f32 v[162:163], v[98:99], v[98:99], v[162:163]
	v_pk_fma_f32 v[160:161], v[104:105], v[104:105], v[160:161]
	v_pk_fma_f32 v[162:163], v[106:107], v[106:107], v[162:163]
	v_pk_fma_f32 v[160:161], v[100:101], v[100:101], v[160:161]
	v_pk_fma_f32 v[162:163], v[102:103], v[102:103], v[162:163]
	v_pk_add_f32 v[160:161], v[160:161], v[162:163]
	v_add_f32_e32 v160, v160, v161
	v_cvt_pk_bf16_f32 v124, v124, v125
	v_cvt_pk_bf16_f32 v125, v126, v127
	v_cvt_pk_bf16_f32 v126, v116, v117
	v_cvt_pk_bf16_f32 v127, v118, v119
	v_cvt_pk_bf16_f32 v112, v112, v113
	v_cvt_pk_bf16_f32 v113, v114, v115
	v_cvt_pk_bf16_f32 v114, v108, v109
	v_cvt_pk_bf16_f32 v115, v110, v111
	v_cvt_pk_bf16_f32 v120, v120, v121
	v_cvt_pk_bf16_f32 v121, v122, v123
	v_cvt_pk_bf16_f32 v122, v96, v97
	v_cvt_pk_bf16_f32 v123, v98, v99
	v_cvt_pk_bf16_f32 v104, v104, v105
	v_cvt_pk_bf16_f32 v105, v106, v107
	v_cvt_pk_bf16_f32 v106, v100, v101
	v_cvt_pk_bf16_f32 v107, v102, v103
	v_mov_b32_e32 v161, v160
	s_nop 1
	v_permlane16_swap_b32 v124, v126
	v_permlane16_swap_b32 v125, v127
	v_permlane16_swap_b32 v112, v114
	v_permlane16_swap_b32 v113, v115
	v_permlane16_swap_b32 v120, v122
	v_permlane16_swap_b32 v121, v123
	v_permlane16_swap_b32 v104, v106
	v_permlane16_swap_b32 v105, v107
	v_permlane16_swap_b32 v160, v161
	global_store_dwordx4 v148, v[124:127], s[40:41]
	global_store_dwordx4 v148, v[112:115], s[40:41] offset:64
	global_store_dwordx4 v148, v[120:123], s[40:41] offset:256
	global_store_dwordx4 v148, v[104:107], s[40:41] offset:320
	v_add_f32_e32 v160, v160, v161
	v_mov_b32_e32 v161, v160
	s_nop 1
	v_permlane32_swap_b32 v160, v161
	s_nop 0
	v_add_f32_e32 v160, v160, v161
	s_and_saveexec_b64 s[54:55], s[52:53]
	global_atomic_add_f32 v152, v160, s[14:15]
	s_mov_b64 exec, s[54:55]
	v_pk_mul_f32 v[164:165], v[88:89], v[88:89]
	v_pk_mul_f32 v[166:167], v[90:91], v[90:91]
	v_pk_fma_f32 v[164:165], v[84:85], v[84:85], v[164:165]
	v_pk_fma_f32 v[166:167], v[86:87], v[86:87], v[166:167]
	v_pk_fma_f32 v[164:165], v[80:81], v[80:81], v[164:165]
	v_pk_fma_f32 v[166:167], v[82:83], v[82:83], v[166:167]
	v_pk_fma_f32 v[164:165], v[76:77], v[76:77], v[164:165]
	v_pk_fma_f32 v[166:167], v[78:79], v[78:79], v[166:167]
	v_pk_fma_f32 v[164:165], v[92:93], v[92:93], v[164:165]
	v_pk_fma_f32 v[166:167], v[94:95], v[94:95], v[166:167]
	v_pk_fma_f32 v[164:165], v[64:65], v[64:65], v[164:165]
	v_pk_fma_f32 v[166:167], v[66:67], v[66:67], v[166:167]
	v_pk_fma_f32 v[164:165], v[72:73], v[72:73], v[164:165]
	v_pk_fma_f32 v[166:167], v[74:75], v[74:75], v[166:167]
	v_pk_fma_f32 v[164:165], v[68:69], v[68:69], v[164:165]
	v_pk_fma_f32 v[166:167], v[70:71], v[70:71], v[166:167]
	v_pk_add_f32 v[164:165], v[164:165], v[166:167]
	v_add_f32_e32 v164, v164, v165
; __device__ __forceinline__ void tok_ss_atomic(float part, float* dst, int fq) {
;   part += __shfl_xor(part, 16);
;   part += __shfl_xor(part, 32);
;   if (fq == 0) atomicAdd(dst, part);
; }
; __device__ void phase5(const Params& p) {
;     ...
;     #pragma unroll
;     for (int bj = 0; bj < 2; ++bj)
;       #pragma unroll
;       for (int n = 0; n < 2; ++n) {
;         const int t = EPI_T(bj, n);
;         float part = 0.f;
;         #pragma unroll
;         for (int ai = 0; ai < 2; ++ai)
;           #pragma unroll
;           for (int m = 0; m < 4; ++m) {
;             const f32x4 v = acc[ai][bj][m][n];
;             part += v[0] * v[0] + v[1] * v[1] + v[2] * v[2] + v[3] * v[3];
;             v2u ov; ov.x = pk2(v[0], v[1]); ov.y = pk2(v[2], v[3]);
;             *reinterpret_cast<v2u*>(o + (size_t)t * D + EPI_F(ai, m)) = ov;
;           }
;         tok_ss_atomic(part, sso + t, fq);
;       }
	v_cvt_pk_bf16_f32 v88, v88, v89
	v_cvt_pk_bf16_f32 v89, v90, v91
	v_cvt_pk_bf16_f32 v90, v84, v85
	v_cvt_pk_bf16_f32 v91, v86, v87
	v_cvt_pk_bf16_f32 v80, v80, v81
	v_cvt_pk_bf16_f32 v81, v82, v83
	v_cvt_pk_bf16_f32 v82, v76, v77
	v_cvt_pk_bf16_f32 v83, v78, v79
	v_cvt_pk_bf16_f32 v92, v92, v93
	v_cvt_pk_bf16_f32 v93, v94, v95
	v_cvt_pk_bf16_f32 v94, v64, v65
	v_cvt_pk_bf16_f32 v95, v66, v67
	v_cvt_pk_bf16_f32 v72, v72, v73
	v_cvt_pk_bf16_f32 v73, v74, v75
	v_cvt_pk_bf16_f32 v74, v68, v69
	v_cvt_pk_bf16_f32 v75, v70, v71
	v_mov_b32_e32 v165, v164
	s_nop 1
	v_permlane16_swap_b32 v88, v90
	v_permlane16_swap_b32 v89, v91
	v_permlane16_swap_b32 v80, v82
	v_permlane16_swap_b32 v81, v83
	v_permlane16_swap_b32 v92, v94
	v_permlane16_swap_b32 v93, v95
	v_permlane16_swap_b32 v72, v74
	v_permlane16_swap_b32 v73, v75
	v_permlane16_swap_b32 v164, v165
	global_store_dwordx4 v149, v[88:91], s[40:41]
	global_store_dwordx4 v149, v[80:83], s[40:41] offset:64
	global_store_dwordx4 v149, v[92:95], s[40:41] offset:256
	global_store_dwordx4 v149, v[72:75], s[40:41] offset:320
	v_add_f32_e32 v164, v164, v165
	v_mov_b32_e32 v165, v164
	s_nop 1
	v_permlane32_swap_b32 v164, v165
	s_nop 0
	v_add_f32_e32 v164, v164, v165
	s_and_saveexec_b64 s[54:55], s[52:53]
	global_atomic_add_f32 v153, v164, s[14:15]
	s_mov_b64 exec, s[54:55]
	v_pk_mul_f32 v[168:169], v[60:61], v[60:61]
	v_pk_mul_f32 v[170:171], v[62:63], v[62:63]
	v_pk_fma_f32 v[168:169], v[52:53], v[52:53], v[168:169]
	v_pk_fma_f32 v[170:171], v[54:55], v[54:55], v[170:171]
	v_pk_fma_f32 v[168:169], v[48:49], v[48:49], v[168:169]
	v_pk_fma_f32 v[170:171], v[50:51], v[50:51], v[170:171]
	v_pk_fma_f32 v[168:169], v[44:45], v[44:45], v[168:169]
	v_pk_fma_f32 v[170:171], v[46:47], v[46:47], v[170:171]
	v_pk_fma_f32 v[168:169], v[56:57], v[56:57], v[168:169]
	v_pk_fma_f32 v[170:171], v[58:59], v[58:59], v[170:171]
	v_pk_fma_f32 v[168:169], v[32:33], v[32:33], v[168:169]
	v_pk_fma_f32 v[170:171], v[34:35], v[34:35], v[170:171]
	v_pk_fma_f32 v[168:169], v[40:41], v[40:41], v[168:169]
	v_pk_fma_f32 v[170:171], v[42:43], v[42:43], v[170:171]
	v_pk_fma_f32 v[168:169], v[36:37], v[36:37], v[168:169]
	v_pk_fma_f32 v[170:171], v[38:39], v[38:39], v[170:171]
	v_pk_add_f32 v[168:169], v[168:169], v[170:171]
	v_add_f32_e32 v168, v168, v169
	v_cvt_pk_bf16_f32 v60, v60, v61
	v_cvt_pk_bf16_f32 v61, v62, v63
	v_cvt_pk_bf16_f32 v62, v52, v53
	v_cvt_pk_bf16_f32 v63, v54, v55
	v_cvt_pk_bf16_f32 v48, v48, v49
	v_cvt_pk_bf16_f32 v49, v50, v51
	v_cvt_pk_bf16_f32 v50, v44, v45
	v_cvt_pk_bf16_f32 v51, v46, v47
	v_cvt_pk_bf16_f32 v56, v56, v57
	v_cvt_pk_bf16_f32 v57, v58, v59
	v_cvt_pk_bf16_f32 v58, v32, v33
	v_cvt_pk_bf16_f32 v59, v34, v35
	v_cvt_pk_bf16_f32 v40, v40, v41
	v_cvt_pk_bf16_f32 v41, v42, v43
	v_cvt_pk_bf16_f32 v42, v36, v37
	v_cvt_pk_bf16_f32 v43, v38, v39
	v_mov_b32_e32 v169, v168
	s_nop 1
	v_permlane16_swap_b32 v60, v62
	v_permlane16_swap_b32 v61, v63
	v_permlane16_swap_b32 v48, v50
	v_permlane16_swap_b32 v49, v51
	v_permlane16_swap_b32 v56, v58
	v_permlane16_swap_b32 v57, v59
	v_permlane16_swap_b32 v40, v42
	v_permlane16_swap_b32 v41, v43
	v_permlane16_swap_b32 v168, v169
	global_store_dwordx4 v150, v[60:63], s[40:41]
	global_store_dwordx4 v150, v[48:51], s[40:41] offset:64
	global_store_dwordx4 v150, v[56:59], s[40:41] offset:256
	global_store_dwordx4 v150, v[40:43], s[40:41] offset:320
	v_add_f32_e32 v168, v168, v169
	v_mov_b32_e32 v169, v168
	s_nop 1
	v_permlane32_swap_b32 v168, v169
	s_nop 0
	v_add_f32_e32 v168, v168, v169
	s_and_saveexec_b64 s[54:55], s[52:53]
	global_atomic_add_f32 v154, v168, s[14:15]
	s_mov_b64 exec, s[54:55]
	v_pk_mul_f32 v[172:173], v[28:29], v[28:29]
	v_pk_mul_f32 v[174:175], v[30:31], v[30:31]
	v_pk_fma_f32 v[172:173], v[20:21], v[20:21], v[172:173]
	v_pk_fma_f32 v[174:175], v[22:23], v[22:23], v[174:175]
	v_pk_fma_f32 v[172:173], v[16:17], v[16:17], v[172:173]
	v_pk_fma_f32 v[174:175], v[18:19], v[18:19], v[174:175]
	v_pk_fma_f32 v[172:173], v[12:13], v[12:13], v[172:173]
	v_pk_fma_f32 v[174:175], v[14:15], v[14:15], v[174:175]
	v_pk_fma_f32 v[172:173], v[24:25], v[24:25], v[172:173]
	v_pk_fma_f32 v[174:175], v[26:27], v[26:27], v[174:175]
	v_pk_fma_f32 v[172:173], v[0:1], v[0:1], v[172:173]
	v_pk_fma_f32 v[174:175], v[2:3], v[2:3], v[174:175]
	v_pk_fma_f32 v[172:173], v[8:9], v[8:9], v[172:173]
	v_pk_fma_f32 v[174:175], v[10:11], v[10:11], v[174:175]
	v_pk_fma_f32 v[172:173], v[4:5], v[4:5], v[172:173]
	v_pk_fma_f32 v[174:175], v[6:7], v[6:7], v[174:175]
	v_pk_add_f32 v[172:173], v[172:173], v[174:175]
	v_add_f32_e32 v172, v172, v173
	v_cvt_pk_bf16_f32 v28, v28, v29
	v_cvt_pk_bf16_f32 v29, v30, v31
	v_cvt_pk_bf16_f32 v30, v20, v21
	v_cvt_pk_bf16_f32 v31, v22, v23
	v_cvt_pk_bf16_f32 v16, v16, v17
	v_cvt_pk_bf16_f32 v17, v18, v19
	v_cvt_pk_bf16_f32 v18, v12, v13
	v_cvt_pk_bf16_f32 v19, v14, v15
	v_cvt_pk_bf16_f32 v24, v24, v25
	v_cvt_pk_bf16_f32 v25, v26, v27
	v_cvt_pk_bf16_f32 v26, v0, v1
	v_cvt_pk_bf16_f32 v27, v2, v3
	v_cvt_pk_bf16_f32 v8, v8, v9
	v_cvt_pk_bf16_f32 v9, v10, v11
	v_cvt_pk_bf16_f32 v10, v4, v5
	v_cvt_pk_bf16_f32 v11, v6, v7
	v_mov_b32_e32 v173, v172
	s_nop 1
	v_permlane16_swap_b32 v28, v30
	v_permlane16_swap_b32 v29, v31
	v_permlane16_swap_b32 v16, v18
	v_permlane16_swap_b32 v17, v19
	v_permlane16_swap_b32 v24, v26
	v_permlane16_swap_b32 v25, v27
	v_permlane16_swap_b32 v8, v10
	v_permlane16_swap_b32 v9, v11
	v_permlane16_swap_b32 v172, v173
	global_store_dwordx4 v151, v[28:31], s[40:41]
	global_store_dwordx4 v151, v[16:19], s[40:41] offset:64
	global_store_dwordx4 v151, v[24:27], s[40:41] offset:256
	global_store_dwordx4 v151, v[8:11], s[40:41] offset:320
	v_add_f32_e32 v172, v172, v173
	v_mov_b32_e32 v173, v172
	s_nop 1
	v_permlane32_swap_b32 v172, v173
	s_nop 0
	v_add_f32_e32 v172, v172, v173
	s_and_saveexec_b64 s[54:55], s[52:53]
	global_atomic_add_f32 v155, v172, s[14:15]
	s_mov_b64 exec, s[54:55]
	s_mov_b64 s[48:49], exec
	s_branch .LBB0_651

; __device__ void phase6(const Params& p) {
;   char* ws = p.ws;
;   const u16* x1h = (const u16*)(ws + OFF_SGA);
;   const u16* ph = (const u16*)(ws + OFF_PH);
;   u16* e = (u16*)(ws + OFF_SGB);
;   float* sse = (float*)(ws + OFF_SSE);
;   constexpr int nM = T / 256, nN = D / 256;
;   f32x4 acc[2][2][4][2];
;   for (int it = 0;; ++it) {
;     int pm, pn;
;     if (!tile_coords(it, nM, nN, pm, pn)) break;
;     const int to = pm * 256, fo = pn * 256;
.LBB0_761:
	s_or_b64 exec, exec, s[0:1]
	s_add_u32 s6, s30, 0x50000
	s_addc_u32 s7, s31, 0
	s_add_u32 s3, s30, 0x3d00000
	s_addc_u32 s51, s31, 0
	s_add_u32 s70, s30, 0x3d00f80
	s_addc_u32 s71, s31, 0
	s_mov_b32 s72, 0
	s_mov_b32 s100, 0
	v_mov_b32_e32 v129, 0
	s_mov_b32 s73, 0x10000
	s_mov_b32 s76, 0x14000
	s_mov_b64 s[0:1], 0x80
	s_mov_b32 s77, 0x18000
	s_mov_b32 s78, 0x1c000
	s_mov_b64 s[8:9], 0x3d80080
	s_mov_b64 s[14:15], 0x26000100
	s_mov_b64 s[16:17], 0x3d00100
	s_mov_b64 s[18:19], 0x26080100
	s_mov_b64 s[20:21], 0x3d80100
	s_mov_b64 s[22:23], 0x26000180
	s_mov_b64 s[38:39], 0x3d00180
	s_mov_b64 s[40:41], 0x26080180
	s_movk_i32 s79, 0x100
	s_mov_b64 s[42:43], 0x4800000
	s_mov_b64 s[44:45], 0x4500000
	s_mov_b64 s[46:47], 0x4810000
	s_mov_b64 s[48:49], 0x4510000
	s_movk_i32 s80, 0x60
	s_mov_b32 s50, 0x3b808081
	v_mov_b32_e32 v141, 1
	s_barrier
	s_branch .LBB0_764

; __device__ __forceinline__ int otid() { int t = threadIdx.x; asm volatile("" : "+v"(t)); return t; }
; #define WAIT_V(n) asm volatile("s_waitcnt vmcnt(" #n ")" ::: "memory")
; #define BAR __builtin_amdgcn_s_barrier()
; __device__ __forceinline__ void gemm_tile(const u16* __restrict__ A, const u16* __restrict__ Bt, const int K,
;                                           const int brow, const int bcol, f32x4 (&acc)[2][2][4][2],
;                                           const bool ZERO_INIT = true) {
;     ...
;   const int tidx = otid();
;   const int wid = tidx >> 6, lane = tidx & 63, wr = wid >> 2, wc = wid & 3, fr = lane & 15, fq = lane >> 4;
;   #pragma unroll
;   for (int a = 0; a < 2; ++a)
;     #pragma unroll
;     for (int b = 0; b < 2; ++b)
;       #pragma unroll
;       for (int m = 0; m < 4; ++m)
;         #pragma unroll
;         for (int n = 0; n < 2; ++n)
;           if (ZERO_INIT) acc[a][b][m][n] = f32x4{0.f, 0.f, 0.f, 0.f};
;   bf16x8 At[4][2], B0[2][2], B1[2][2];
;   const int nt = K / BK;
;   const unsigned ldsw = (unsigned)__builtin_amdgcn_readfirstlane(wid) * 1024u;
;   unsigned vo0, vo1;
;   {
;     int r0, c0, r1, c1;
;     stage_rc(tidx * 16, r0, c0);
;     stage_rc(tidx * 16 + 8192, r1, c1);
;     vo0 = (unsigned)(r0 * K + c0) * 2u;
;     vo1 = (unsigned)(r1 * K + c1) * 2u;
;   }
;   STAGE(SB(0, 0), Bt, bcol, 0); STAGE(SA(0, 0), A, brow, 0);
;   STAGE(SB(0, 1), Bt, bcol + HALF, 0); STAGE(SA(0, 1), A, brow + HALF, 0);
;   if (wr == 1) BAR;
;   WAIT_V(4); BAR;
;   STAGE(SB(1, 0), Bt, bcol, 1); STAGE(SA(1, 0), A, brow, 1); STAGE(SB(1, 1), Bt, bcol + HALF, 1);
.LBB0_767:
	s_mul_i32 s25, s72, s33
	s_add_i32 s24, s24, s25
	s_cmpk_gt_i32 s24, 0x4ff
	s_mov_b64 s[52:53], -1
	s_cbranch_scc1 .LBB0_763
	v_mov_b32_e32 v142, v194
	v_mov_b32_e32 v143, v194
	s_ashr_i32 s25, s24, 31
	v_bfe_i32 v2, v143, 27, 1
	v_lshlrev_b32_e32 v5, 4, v143
	v_lshrrev_b32_e32 v2, 22, v2
	v_add_u32_e32 v2, v5, v2
	v_and_b32_e32 v2, 0xfffffc00, v2
	v_sub_u32_e32 v2, v5, v2
	s_lshr_b32 s25, s25, 26
	v_lshrrev_b32_e32 v3, 4, v2
	s_add_i32 s25, s24, s25
	v_bitop3_b32 v4, v3, v2, 32 bitop3:0x6c
	v_ashrrev_i32_e32 v2, 31, v2
	s_and_b32 s52, s25, 0xffc0
	v_lshrrev_b32_e32 v2, 26, v2
	s_sub_i32 s24, s24, s52
	v_add_u32_e32 v2, v4, v2
	s_bfe_i32 s52, s24, 0x80000
	v_ashrrev_i32_e32 v2, 6, v2
	s_bfe_u32 s52, s52, 0x3000c
	v_mul_i32_i24_e32 v6, 64, v2
	s_add_i32 s52, s24, s52
	v_sub_u32_e32 v4, v4, v6
	v_add_u32_e32 v6, 0x2000, v5
	s_bfe_i32 s53, s52, 0x80000
	s_and_b32 s52, s52, 0xf8
	v_ashrrev_i32_e32 v5, 31, v6
	s_sub_i32 s24, s24, s52
	v_lshrrev_b32_e32 v5, 22, v5
	s_sext_i32_i8 s24, s24
	s_lshl_b32 s25, s25, 5
	v_add_u32_e32 v5, v6, v5
	s_sext_i32_i16 s53, s53
	s_and_b32 s25, s25, 0xfffff800
	s_lshl_b32 s24, s24, 8
	v_ashrrev_i32_e32 v5, 10, v5
	s_add_i32 s54, s24, s25
	s_lshl_b32 s24, s53, 5
	s_waitcnt lgkmcnt(0)
	v_ashrrev_i32_e32 v1, 6, v143
	v_mul_i32_i24_e32 v7, 0x400, v5
	s_and_b32 s52, s24, 0xffffff00
	v_readfirstlane_b32 s24, v1
	v_ashrrev_i32_e32 v0, 31, v143
	v_sub_u32_e32 v6, v6, v7
	s_ashr_i32 s55, s54, 31
	s_lshl_b32 s81, s24, 10
	v_lshrrev_b32_e32 v0, 26, v0
	v_lshrrev_b32_e32 v7, 4, v6
	s_lshl_b64 s[58:59], s[54:55], 12
	v_add_u32_e32 v0, v143, v0
	v_bitop3_b32 v8, v7, v6, 32 bitop3:0x6c
	v_lshlrev_b32_e32 v6, 3, v5
	s_add_u32 s62, s10, s58
	v_ashrrev_i32_e32 v0, 6, v0
	v_and_b32_e32 v7, 0xffff0, v6
	v_ashrrev_i32_e32 v6, 31, v8
	s_addc_u32 s63, s11, s59
	s_ashr_i32 s53, s52, 31
	v_lshlrev_b32_e32 v3, 3, v0
	v_lshrrev_b32_e32 v6, 26, v6
	s_add_i32 s82, s81, 0x10000
	s_add_i32 s83, s81, 0x12000
	s_lshl_b64 s[60:61], s[52:53], 12
	v_and_b32_e32 v3, 0xffff0, v3
	v_add_u32_e32 v10, v8, v6
	s_add_u32 s64, s3, s60
	v_add_u32_e32 v9, v2, v3
	v_lshlrev_b32_e32 v3, 5, v0
	v_ashrrev_i32_e32 v6, 6, v10
	v_and_b32_e32 v10, 0xc0, v10
	s_addc_u32 s65, s51, s61
	s_or_b32 s24, s54, 0x80
	v_and_b32_e32 v3, 32, v3
	v_ashrrev_i16_sdwa v4, v141, sext(v4) dst_sel:DWORD dst_unused:UNUSED_PAD src0_sel:DWORD src1_sel:BYTE_0
	v_add_u32_e32 v11, v6, v7
	v_lshlrev_b32_e32 v7, 5, v5
	v_sub_u32_e32 v8, v8, v10
	s_ashr_i32 s25, s24, 31
	v_bfe_i32 v4, v4, 0, 16
	v_and_b32_e32 v7, 32, v7
	v_ashrrev_i16_sdwa v8, v141, sext(v8) dst_sel:DWORD dst_unused:UNUSED_PAD src0_sel:DWORD src1_sel:BYTE_0
	v_lshl_or_b32 v9, v9, 11, v3
	s_add_i32 s84, s81, 0x2000
	s_lshl_b64 s[24:25], s[24:25], 12
	v_bfe_i32 v8, v8, 0, 16
	v_add_lshl_u32 v128, v9, v4, 1
	v_lshl_or_b32 v9, v11, 11, v7
	s_add_u32 s66, s10, s24
	s_addc_u32 s67, s11, s25
	v_add_lshl_u32 v130, v9, v8, 1
	s_or_b32 s24, s52, 0x80
	s_ashr_i32 s25, s24, 31
	s_add_i32 s85, s81, 0x14000
	s_add_i32 s89, s81, 0x16000
	s_lshl_b64 s[56:57], s[24:25], 12
	s_add_u32 s68, s3, s56
	s_addc_u32 s69, s51, s57
	s_add_i32 s24, s81, 0x4000
	s_add_i32 s25, s81, 0x6000
	v_ashrrev_i32_e32 v9, 8, v143
	v_mov_b32_e32 v250, v128
	v_mov_b32_e32 v251, v130
	s_cmp_eq_u32 s100, 1
	s_cbranch_scc1 .Lp6_pf_skip
	s_mov_b32 m0, s82
	s_nop 0
	global_load_lds_dwordx4 v128, s[62:63]
	s_mov_b32 m0, s83
	s_nop 0
	global_load_lds_dwordx4 v130, s[62:63]
	s_mov_b32 m0, s81
	s_nop 0
	global_load_lds_dwordx4 v128, s[64:65]
	s_mov_b32 m0, s84
	s_nop 0
	global_load_lds_dwordx4 v130, s[64:65]
	s_mov_b32 m0, s85
	s_nop 0
	global_load_lds_dwordx4 v128, s[66:67]
	s_mov_b32 m0, s89
	s_nop 0
	global_load_lds_dwordx4 v130, s[66:67]
	s_mov_b32 m0, s24
	s_nop 0
	global_load_lds_dwordx4 v128, s[68:69]
	s_mov_b32 m0, s25
	s_nop 0
	global_load_lds_dwordx4 v130, s[68:69]
.Lp6_pf_skip:
	v_cmp_eq_u32_e32 vcc, 1, v9
	s_and_saveexec_b64 s[68:69], vcc
	s_cbranch_execz .LBB0_770
	s_barrier
.LBB0_770:
	s_or_b64 exec, exec, s[68:69]
	v_mov_b32_e32 v131, v129
	v_lshl_add_u64 v[10:11], s[62:63], 0, v[128:129]
	v_lshl_add_u64 v[12:13], s[62:63], 0, v[130:131]
	s_add_i32 s62, s81, 0x18000
	v_lshl_add_u64 v[10:11], v[10:11], 0, s[0:1]
	s_mov_b32 m0, s62
	s_add_i32 s63, s81, 0x1a000
	v_lshl_add_u64 v[14:15], s[64:65], 0, v[128:129]
	v_lshl_add_u64 v[16:17], s[64:65], 0, v[130:131]
	s_cmp_eq_u32 s100, 1
	s_cbranch_scc1 .Lp6_w1_pf
	s_waitcnt vmcnt(4)
	s_branch .Lp6_w1_done
.Lp6_w1_pf:
	s_waitcnt vmcnt(40)
; #define WAIT_V(n) asm volatile("s_waitcnt vmcnt(" #n ")" ::: "memory")
; #define BAR __builtin_amdgcn_s_barrier()
; __device__ __forceinline__ void gemm_tile(const u16* __restrict__ A, const u16* __restrict__ Bt, const int K,
;                                           const int brow, const int bcol, f32x4 (&acc)[2][2][4][2],
;                                           const bool ZERO_INIT = true) {
;     ...
;   #pragma unroll
;   for (int a = 0; a < 2; ++a)
;     #pragma unroll
;     for (int b = 0; b < 2; ++b)
;       #pragma unroll
;       for (int m = 0; m < 4; ++m)
;         #pragma unroll
;         for (int n = 0; n < 2; ++n)
;           if (ZERO_INIT) acc[a][b][m][n] = f32x4{0.f, 0.f, 0.f, 0.f};
;   bf16x8 At[4][2], B0[2][2], B1[2][2];
;   const int nt = K / BK;
;   const unsigned ldsw = (unsigned)__builtin_amdgcn_readfirstlane(wid) * 1024u;
;   unsigned vo0, vo1;
;   {
;     int r0, c0, r1, c1;
;     stage_rc(tidx * 16, r0, c0);
;     stage_rc(tidx * 16 + 8192, r1, c1);
;     vo0 = (unsigned)(r0 * K + c0) * 2u;
;     vo1 = (unsigned)(r1 * K + c1) * 2u;
;   }
;   STAGE(SB(0, 0), Bt, bcol, 0); STAGE(SA(0, 0), A, brow, 0);
;   STAGE(SB(0, 1), Bt, bcol + HALF, 0); STAGE(SA(0, 1), A, brow + HALF, 0);
;   if (wr == 1) BAR;
;   WAIT_V(4); BAR;
;   STAGE(SB(1, 0), Bt, bcol, 1); STAGE(SA(1, 0), A, brow, 1); STAGE(SB(1, 1), Bt, bcol + HALF, 1);
;   WAIT_V(6); BAR;
.Lp6_w1_done:
	s_barrier
	global_load_lds_dwordx4 v[10:11], off
	v_lshl_add_u64 v[10:11], v[12:13], 0, s[0:1]
	s_mov_b32 m0, s63
	s_add_i32 s64, s81, 0x8000
	global_load_lds_dwordx4 v[10:11], off
	v_lshl_add_u64 v[10:11], v[14:15], 0, s[0:1]
	s_mov_b32 m0, s64
	s_add_i32 s65, s81, 0xa000
	v_lshl_add_u64 v[18:19], s[66:67], 0, v[128:129]
	v_lshl_add_u64 v[20:21], s[66:67], 0, v[130:131]
	global_load_lds_dwordx4 v[10:11], off
	v_lshl_add_u64 v[10:11], v[16:17], 0, s[0:1]
	s_mov_b32 m0, s65
	s_add_i32 s66, s81, 0x1c000
	global_load_lds_dwordx4 v[10:11], off
	v_lshl_add_u64 v[10:11], v[18:19], 0, s[0:1]
	s_mov_b32 m0, s66
	s_add_i32 s67, s81, 0x1e000
	global_load_lds_dwordx4 v[10:11], off
	v_lshl_add_u64 v[10:11], v[20:21], 0, s[0:1]
	s_mov_b32 m0, s67
	v_lshlrev_b32_e32 v0, 14, v0
	global_load_lds_dwordx4 v[10:11], off
	v_and_b32_e32 v22, 15, v143
	v_lshlrev_b32_e32 v1, 12, v1
	v_lshlrev_b32_e32 v12, 2, v143
	v_and_b32_e32 v0, 0x7fff8000, v0
	v_and_b32_e32 v23, 48, v143
	v_and_b32_e32 v10, 0x3000, v1
	v_lshlrev_b32_e32 v1, 6, v22
	v_and_b32_e32 v12, 32, v12
	v_lshl_add_u32 v0, v2, 11, v0
	v_lshlrev_b32_e32 v2, 14, v5
	v_or_b32_e32 v11, v1, v23
	v_bitop3_b32 v13, v1, v12, v23 bitop3:0x36
	v_lshlrev_b32_e32 v1, 6, v143
	v_and_b32_e32 v2, 0x7fff8000, v2
	v_and_b32_e32 v1, 0x3c0, v1
	v_or_b32_e32 v0, v0, v3
	v_lshl_add_u32 v2, v6, 11, v2
	s_cmp_eq_u32 s100, 1
	s_cbranch_scc1 .Lp6_w2_pf
	s_waitcnt vmcnt(6)
	s_branch .Lp6_w2_done
.Lp6_w2_pf:
	s_waitcnt vmcnt(42)
.Lp6_w2_done:
	v_bitop3_b32 v14, v11, s73, v12 bitop3:0xde
	v_bitop3_b32 v15, v11, s76, v12 bitop3:0xde
	v_bitop3_b32 v16, v11, s77, v12 bitop3:0xde
	v_bitop3_b32 v11, v11, s78, v12 bitop3:0xde
	v_lshlrev_b32_e32 v9, 13, v9
	v_bitop3_b32 v12, v1, v12, v23 bitop3:0x36
	v_add_lshl_u32 v0, v0, v4, 1
	v_mov_b32_e32 v1, v129
	v_or_b32_e32 v2, v2, v7
	v_or_b32_e32 v17, 0x800, v9
	v_or_b32_e32 v18, 0x1000, v9
	v_or_b32_e32 v19, 0x1800, v9
	v_lshl_add_u64 v[132:133], s[58:59], 0, v[0:1]
	v_add_lshl_u32 v2, v2, v8, 1
	v_mov_b32_e32 v3, v129
	v_lshl_add_u64 v[136:137], s[60:61], 0, v[0:1]
	v_mov_b32_e32 v0, 0
	v_lshl_add_u64 v[134:135], s[58:59], 0, v[2:3]
	v_lshl_add_u64 v[138:139], s[60:61], 0, v[2:3]
	s_mov_b32 s61, -2
	v_add_u32_e32 v151, v14, v10
	v_add_u32_e32 v147, v13, v9
	v_add_u32_e32 v146, v12, v17
	v_add_u32_e32 v145, v12, v18
	v_add_u32_e32 v144, v12, v19
	s_add_i32 s68, s81, 0xc000
	s_add_i32 s60, s81, 0xe000
	v_add_u32_e32 v150, v15, v10
	v_add_u32_e32 v149, v16, v10
	v_add_u32_e32 v148, v11, v10
	s_mov_b64 s[58:59], s[30:31]
	v_mov_b32_e32 v1, v0
	v_mov_b32_e32 v2, v0
	v_mov_b32_e32 v3, v0
	v_mov_b32_e32 v4, v0
	v_mov_b32_e32 v5, v0
	v_mov_b32_e32 v6, v0
	v_mov_b32_e32 v7, v0
	v_mov_b32_e32 v8, v0
	v_mov_b32_e32 v9, v0
	v_mov_b32_e32 v10, v0
	v_mov_b32_e32 v11, v0
	v_mov_b32_e32 v12, v0
	v_mov_b32_e32 v13, v0
	v_mov_b32_e32 v14, v0
	v_mov_b32_e32 v15, v0
	v_mov_b32_e32 v16, v0
	v_mov_b32_e32 v17, v0
	v_mov_b32_e32 v18, v0
	v_mov_b32_e32 v19, v0
	v_mov_b32_e32 v20, v0
	v_mov_b32_e32 v21, v0
	v_mov_b32_e32 v22, v0
	v_mov_b32_e32 v23, v0
	v_mov_b32_e32 v24, v0
	v_mov_b32_e32 v25, v0
	v_mov_b32_e32 v26, v0
	v_mov_b32_e32 v27, v0
	v_mov_b32_e32 v28, v0
	v_mov_b32_e32 v29, v0
	v_mov_b32_e32 v30, v0
	v_mov_b32_e32 v31, v0
	v_mov_b32_e32 v32, v0
	v_mov_b32_e32 v33, v0
	v_mov_b32_e32 v34, v0
	v_mov_b32_e32 v35, v0
	v_mov_b32_e32 v36, v0
	v_mov_b32_e32 v37, v0
	v_mov_b32_e32 v38, v0
	v_mov_b32_e32 v39, v0
	v_mov_b32_e32 v40, v0
	v_mov_b32_e32 v41, v0
	v_mov_b32_e32 v42, v0
	v_mov_b32_e32 v43, v0
	v_mov_b32_e32 v44, v0
	v_mov_b32_e32 v45, v0
	v_mov_b32_e32 v46, v0
	v_mov_b32_e32 v47, v0
	v_mov_b32_e32 v48, v0
	v_mov_b32_e32 v49, v0
	v_mov_b32_e32 v50, v0
	v_mov_b32_e32 v51, v0
	v_mov_b32_e32 v52, v0
	v_mov_b32_e32 v53, v0
	v_mov_b32_e32 v54, v0
	v_mov_b32_e32 v55, v0
	v_mov_b32_e32 v56, v0
	v_mov_b32_e32 v57, v0
	v_mov_b32_e32 v58, v0
	v_mov_b32_e32 v59, v0
	v_mov_b32_e32 v60, v0
	v_mov_b32_e32 v61, v0
	v_mov_b32_e32 v62, v0
	v_mov_b32_e32 v63, v0
	v_mov_b32_e32 v64, v0
	v_mov_b32_e32 v65, v0
	v_mov_b32_e32 v66, v0
	v_mov_b32_e32 v67, v0
	v_mov_b32_e32 v68, v0
	v_mov_b32_e32 v69, v0
	v_mov_b32_e32 v70, v0
	v_mov_b32_e32 v71, v0
	v_mov_b32_e32 v72, v0
	v_mov_b32_e32 v73, v0
	v_mov_b32_e32 v74, v0
	v_mov_b32_e32 v75, v0
	v_mov_b32_e32 v76, v0
	v_mov_b32_e32 v77, v0
	v_mov_b32_e32 v78, v0
	v_mov_b32_e32 v79, v0
	v_mov_b32_e32 v80, v0
	v_mov_b32_e32 v81, v0
	v_mov_b32_e32 v82, v0
	v_mov_b32_e32 v83, v0
	v_mov_b32_e32 v84, v0
	v_mov_b32_e32 v85, v0
	v_mov_b32_e32 v86, v0
	v_mov_b32_e32 v87, v0
	v_mov_b32_e32 v88, v0
	v_mov_b32_e32 v89, v0
	v_mov_b32_e32 v90, v0
	v_mov_b32_e32 v91, v0
	v_mov_b32_e32 v92, v0
	v_mov_b32_e32 v93, v0
	v_mov_b32_e32 v94, v0
	v_mov_b32_e32 v95, v0
	v_mov_b32_e32 v96, v0
	v_mov_b32_e32 v97, v0
	v_mov_b32_e32 v98, v0
	v_mov_b32_e32 v99, v0
	v_mov_b32_e32 v100, v0
	v_mov_b32_e32 v101, v0
	v_mov_b32_e32 v102, v0
	v_mov_b32_e32 v103, v0
	v_mov_b32_e32 v104, v0
	v_mov_b32_e32 v105, v0
	v_mov_b32_e32 v106, v0
	v_mov_b32_e32 v107, v0
	v_mov_b32_e32 v108, v0
	v_mov_b32_e32 v109, v0
	v_mov_b32_e32 v110, v0
	v_mov_b32_e32 v111, v0
	v_mov_b32_e32 v112, v0
	v_mov_b32_e32 v113, v0
	v_mov_b32_e32 v114, v0
	v_mov_b32_e32 v115, v0
	v_mov_b32_e32 v116, v0
	v_mov_b32_e32 v117, v0
	v_mov_b32_e32 v118, v0
	v_mov_b32_e32 v119, v0
	v_mov_b32_e32 v120, v0
	v_mov_b32_e32 v121, v0
	v_mov_b32_e32 v122, v0
	v_mov_b32_e32 v123, v0
	v_mov_b32_e32 v124, v0
	v_mov_b32_e32 v125, v0
	v_mov_b32_e32 v126, v0
	v_mov_b32_e32 v127, v0
	s_barrier

; #define WAIT_V(n) asm volatile("s_waitcnt vmcnt(" #n ")" ::: "memory")
; #define WAIT_L(n) asm volatile("s_waitcnt lgkmcnt(" #n ")" ::: "memory")
; #define BAR __builtin_amdgcn_s_barrier()
; #define SCHED __builtin_amdgcn_sched_barrier(0)
; __device__ __forceinline__ void gemm_small(const u16* __restrict__ A, const u16* __restrict__ Bt, const int K,
;                                            const int brow, const int bcol, f32x4 (&acc)[2][2][4][2]) {
;     ...
;   const int nt = K / BK;
;   #pragma unroll 1
;   for (int kt = 0; kt < nt; ++kt) {
;     STAGE(SB(0, 0), Bt, bcol, kt); STAGE(SA(0, 0), A, brow, kt);
;     STAGE(SB(0, 1), Bt, bcol + HALF, kt); STAGE(SA(0, 1), A, brow + HALF, kt);
;     WAIT_V(0); BAR;
;     LDB(B0, 0, 0); LDA(At, 0, 0); LDB(B1, 0, 1);
;     WAIT_L(0); SCHED;
;     MMA(0, 0, At, B0); MMA(0, 1, At, B1);
;     LDA(At, 0, 1);
;     WAIT_L(0); SCHED;
;     MMA(1, 0, At, B0); MMA(1, 1, At, B1);
;     BAR;
;   }
.LBB0_775:
	v_lshl_add_u64 v[148:149], v[130:131], 0, s[56:57]
	v_lshl_add_u64 v[150:151], v[148:149], 0, s[42:43]
	s_add_i32 m0, s24, 0x10000
	v_lshl_add_u64 v[148:149], v[148:149], 0, s[46:47]
	global_load_lds_dwordx4 v[150:151], off
	v_lshl_add_u64 v[150:151], v[132:133], 0, s[56:57]
	v_lshl_add_u64 v[152:153], v[150:151], 0, s[42:43]
	s_add_i32 m0, s24, 0x12000
	s_nop 0
	global_load_lds_dwordx4 v[152:153], off
	v_lshl_add_u64 v[152:153], v[134:135], 0, s[56:57]
	v_lshl_add_u64 v[154:155], v[152:153], 0, s[44:45]
	s_mov_b32 m0, s24
	s_nop 0
	global_load_lds_dwordx4 v[154:155], off
	v_lshl_add_u64 v[154:155], v[136:137], 0, s[56:57]
	v_lshl_add_u64 v[156:157], v[154:155], 0, s[44:45]
	s_add_i32 m0, s24, 0x2000
	s_nop 0
	global_load_lds_dwordx4 v[156:157], off
	s_add_i32 m0, s24, 0x14000
	s_nop 0
	global_load_lds_dwordx4 v[148:149], off
	v_lshl_add_u64 v[148:149], v[150:151], 0, s[46:47]
	s_add_i32 m0, s24, 0x16000
	s_nop 0
	global_load_lds_dwordx4 v[148:149], off
	v_lshl_add_u64 v[148:149], v[152:153], 0, s[48:49]
	s_add_i32 m0, s24, 0x4000
	s_nop 0
	global_load_lds_dwordx4 v[148:149], off
	v_lshl_add_u64 v[148:149], v[154:155], 0, s[48:49]
	s_add_i32 m0, s24, 0x6000
	s_nop 0
	global_load_lds_dwordx4 v[148:149], off
	s_waitcnt vmcnt(0)
	s_barrier
	ds_read_b128 v[148:151], v128
	ds_read_b128 v[152:155], v128 offset:1024
	ds_read_b128 v[156:159], v128 offset:2048
	ds_read_b128 v[160:163], v128 offset:3072
	ds_read_b128 v[164:167], v143
	ds_read_b128 v[168:171], v143 offset:1024
	ds_read_b128 v[172:175], v144
	ds_read_b128 v[176:179], v144 offset:1024
	ds_read_b128 v[180:183], v145
	ds_read_b128 v[184:187], v145 offset:1024
	ds_read_b128 v[188:191], v146
	ds_read_b128 v[196:199], v146 offset:1024
	ds_read_b128 v[200:203], v147
	ds_read_b128 v[204:207], v147 offset:1024
	ds_read_b128 v[208:211], v147 offset:2048
	ds_read_b128 v[212:215], v147 offset:3072
	s_waitcnt lgkmcnt(0)
	s_setprio 1
	s_waitcnt lgkmcnt(0)
	v_mfma_f32_16x16x32_bf16 v[124:127], v[164:167], v[148:151], v[124:127]
	v_mfma_f32_16x16x32_bf16 v[92:95], v[164:167], v[156:159], v[92:95]
	v_mfma_f32_16x16x32_bf16 v[120:123], v[172:175], v[148:151], v[120:123]
	v_mfma_f32_16x16x32_bf16 v[88:91], v[172:175], v[156:159], v[88:91]
	v_mfma_f32_16x16x32_bf16 v[116:119], v[180:183], v[148:151], v[116:119]
	v_mfma_f32_16x16x32_bf16 v[84:87], v[180:183], v[156:159], v[84:87]
	v_mfma_f32_16x16x32_bf16 v[112:115], v[188:191], v[148:151], v[112:115]
	v_mfma_f32_16x16x32_bf16 v[80:83], v[188:191], v[156:159], v[80:83]
	v_mfma_f32_16x16x32_bf16 v[124:127], v[168:171], v[152:155], v[124:127]
	v_mfma_f32_16x16x32_bf16 v[92:95], v[168:171], v[160:163], v[92:95]
	v_mfma_f32_16x16x32_bf16 v[120:123], v[176:179], v[152:155], v[120:123]
	v_mfma_f32_16x16x32_bf16 v[88:91], v[176:179], v[160:163], v[88:91]
	v_mfma_f32_16x16x32_bf16 v[116:119], v[184:187], v[152:155], v[116:119]
	v_mfma_f32_16x16x32_bf16 v[84:87], v[184:187], v[160:163], v[84:87]
	v_mfma_f32_16x16x32_bf16 v[112:115], v[196:199], v[152:155], v[112:115]
	v_mfma_f32_16x16x32_bf16 v[80:83], v[196:199], v[160:163], v[80:83]
	s_setprio 0
	s_setprio 1
	v_mfma_f32_16x16x32_bf16 v[60:63], v[164:167], v[200:203], v[60:63]
	v_mfma_f32_16x16x32_bf16 v[28:31], v[164:167], v[208:211], v[28:31]
	v_mfma_f32_16x16x32_bf16 v[56:59], v[172:175], v[200:203], v[56:59]
	v_mfma_f32_16x16x32_bf16 v[24:27], v[172:175], v[208:211], v[24:27]
	v_mfma_f32_16x16x32_bf16 v[52:55], v[180:183], v[200:203], v[52:55]
	v_mfma_f32_16x16x32_bf16 v[20:23], v[180:183], v[208:211], v[20:23]
	v_mfma_f32_16x16x32_bf16 v[48:51], v[188:191], v[200:203], v[48:51]
	v_mfma_f32_16x16x32_bf16 v[16:19], v[188:191], v[208:211], v[16:19]
	v_mfma_f32_16x16x32_bf16 v[60:63], v[168:171], v[204:207], v[60:63]
	v_mfma_f32_16x16x32_bf16 v[28:31], v[168:171], v[212:215], v[28:31]
	v_mfma_f32_16x16x32_bf16 v[56:59], v[176:179], v[204:207], v[56:59]
	v_mfma_f32_16x16x32_bf16 v[24:27], v[176:179], v[212:215], v[24:27]
	v_mfma_f32_16x16x32_bf16 v[52:55], v[184:187], v[204:207], v[52:55]
	v_mfma_f32_16x16x32_bf16 v[20:23], v[184:187], v[212:215], v[20:23]
	v_mfma_f32_16x16x32_bf16 v[48:51], v[196:199], v[204:207], v[48:51]
	v_mfma_f32_16x16x32_bf16 v[16:19], v[196:199], v[212:215], v[16:19]
	s_setprio 0
	ds_read_b128 v[164:167], v143 offset:16384
	ds_read_b128 v[168:171], v143 offset:17408
	ds_read_b128 v[172:175], v144 offset:16384
	ds_read_b128 v[176:179], v144 offset:17408
	ds_read_b128 v[180:183], v145 offset:16384
	ds_read_b128 v[184:187], v145 offset:17408
	ds_read_b128 v[188:191], v146 offset:16384
	ds_read_b128 v[196:199], v146 offset:17408
	s_waitcnt lgkmcnt(0)
	s_setprio 1
	s_waitcnt lgkmcnt(0)
	v_mfma_f32_16x16x32_bf16 v[108:111], v[164:167], v[148:151], v[108:111]
	v_mfma_f32_16x16x32_bf16 v[76:79], v[164:167], v[156:159], v[76:79]
	v_mfma_f32_16x16x32_bf16 v[104:107], v[172:175], v[148:151], v[104:107]
	v_mfma_f32_16x16x32_bf16 v[72:75], v[172:175], v[156:159], v[72:75]
	v_mfma_f32_16x16x32_bf16 v[100:103], v[180:183], v[148:151], v[100:103]
	v_mfma_f32_16x16x32_bf16 v[68:71], v[180:183], v[156:159], v[68:71]
	v_mfma_f32_16x16x32_bf16 v[96:99], v[188:191], v[148:151], v[96:99]
	v_mfma_f32_16x16x32_bf16 v[64:67], v[188:191], v[156:159], v[64:67]
	v_mfma_f32_16x16x32_bf16 v[108:111], v[168:171], v[152:155], v[108:111]
	v_mfma_f32_16x16x32_bf16 v[76:79], v[168:171], v[160:163], v[76:79]
	v_mfma_f32_16x16x32_bf16 v[104:107], v[176:179], v[152:155], v[104:107]
	v_mfma_f32_16x16x32_bf16 v[72:75], v[176:179], v[160:163], v[72:75]
	v_mfma_f32_16x16x32_bf16 v[100:103], v[184:187], v[152:155], v[100:103]
	v_mfma_f32_16x16x32_bf16 v[68:71], v[184:187], v[160:163], v[68:71]
	v_mfma_f32_16x16x32_bf16 v[96:99], v[196:199], v[152:155], v[96:99]
	v_mfma_f32_16x16x32_bf16 v[64:67], v[196:199], v[160:163], v[64:67]
	s_setprio 0
	s_setprio 1
	v_mfma_f32_16x16x32_bf16 v[44:47], v[164:167], v[200:203], v[44:47]
	v_mfma_f32_16x16x32_bf16 v[12:15], v[164:167], v[208:211], v[12:15]
	v_mfma_f32_16x16x32_bf16 v[40:43], v[172:175], v[200:203], v[40:43]
	v_mfma_f32_16x16x32_bf16 v[8:11], v[172:175], v[208:211], v[8:11]
	v_mfma_f32_16x16x32_bf16 v[36:39], v[180:183], v[200:203], v[36:39]
	v_mfma_f32_16x16x32_bf16 v[4:7], v[180:183], v[208:211], v[4:7]
	v_mfma_f32_16x16x32_bf16 v[32:35], v[188:191], v[200:203], v[32:35]
	v_mfma_f32_16x16x32_bf16 v[0:3], v[188:191], v[208:211], v[0:3]
	v_mfma_f32_16x16x32_bf16 v[44:47], v[168:171], v[204:207], v[44:47]
	v_mfma_f32_16x16x32_bf16 v[12:15], v[168:171], v[212:215], v[12:15]
	v_mfma_f32_16x16x32_bf16 v[40:43], v[176:179], v[204:207], v[40:43]
	v_mfma_f32_16x16x32_bf16 v[8:11], v[176:179], v[212:215], v[8:11]
	v_mfma_f32_16x16x32_bf16 v[36:39], v[184:187], v[204:207], v[36:39]
	v_mfma_f32_16x16x32_bf16 v[4:7], v[184:187], v[212:215], v[4:7]
	v_mfma_f32_16x16x32_bf16 v[32:35], v[196:199], v[204:207], v[32:35]
	v_mfma_f32_16x16x32_bf16 v[0:3], v[196:199], v[212:215], v[0:3]
	s_setprio 0
	s_add_u32 s56, s56, 0x80
	s_addc_u32 s57, s57, 0
	s_cmpk_lg_i32 s56, 0x200
	s_barrier
; __device__ __forceinline__ float u8f(unsigned w, int i) { return (float)((w >> (8 * i)) & 0xffu) * (1.f / 255.f); }
; #define EPI_BEGIN_S int fo_e = fo, to_e = to; asm volatile("" : "+s"(fo_e), "+s"(to_e));
; __device__ __forceinline__ bool tile_coords(int it, int nM, int nN, int& pm, int& pn) {
;   const int G = gridDim.x, b = blockIdx.x, ntiles = nM * nN;
;   int L;
;   if ((G & 7) == 0 && (it + 1) * G <= ntiles) L = it * G + (b & 7) * (G >> 3) + (b >> 3);
;   else L = it * G + b;
;   if (L >= ntiles) return false;
;   const int nig = 8 * nN, gid = L / nig, fm = gid * 8, gsz = min(nM - fm, 8);
;   pm = fm + (L % nig) % gsz;
;   pn = (L % nig) / gsz;
;   return true;
; __device__ void phase6(const Params& p) {
;     ...
;     { EPI_BEGIN_S
;       const unsigned* park0 = reinterpret_cast<const unsigned*>(g_smem + 32768) + tid_e;
;       const unsigned* park1 = reinterpret_cast<const unsigned*>(g_smem + 98304) + tid_e;
;       #pragma unroll
;       for (int bj = 0; bj < 2; ++bj)
;         #pragma unroll
;         for (int n = 0; n < 2; ++n) {
;           const int t = EPI_T(bj, n);
;           const size_t rowo = (size_t)t * D;
;           float part = 0.f;
;           #pragma unroll
;           for (int ai = 0; ai < 2; ++ai)
;             #pragma unroll
;             for (int m = 0; m < 4; ++m) {
;               const size_t gi = rowo + EPI_F(ai, m);
;               const int i = ((bj * 2 + n) * 2 + ai) * 4 + m;
;               const unsigned g = (i < 16) ? park0[i * 512] : park1[(i - 16) * 512];
;               const float v0 = acc[ai][bj][m][n][0] * u8f(g, 0), v1 = acc[ai][bj][m][n][1] * u8f(g, 1);
;               const float v2 = acc[ai][bj][m][n][2] * u8f(g, 2), v3 = acc[ai][bj][m][n][3] * u8f(g, 3);
;               part += v0 * v0 + v1 * v1 + v2 * v2 + v3 * v3;
;               v2u ov; ov.x = pk2(v0, v1); ov.y = pk2(v2, v3);
;               *reinterpret_cast<v2u*>(e + gi) = ov;
;             }
;           tok_ss_atomic(part, sse + t, fq);
	s_cbranch_scc1 .LBB0_775
	s_add_i32 s24, s72, 1
	s_mul_i32 s25, s24, s33
	s_add_i32 s55, s25, s33
	s_mov_b32 s56, s2
	s_and_b32 s57, s33, 7
	s_cmp_lg_u32 s57, 0
	s_cbranch_scc1 .Lp6n_base
	s_cmpk_gt_i32 s55, 0x500
	s_cbranch_scc1 .Lp6n_base
	s_mov_b32 s56, s35
.Lp6n_base:
	s_add_i32 s24, s56, s25
	s_mov_b32 s100, 0
	s_cmpk_gt_i32 s24, 0x4ff
	s_cbranch_scc1 .Lp6n_done
	s_lshr_b32 s25, s24, 6
	s_and_b32 s55, s24, 7
	s_lshl_b32 s25, s25, 3
	s_add_i32 s25, s25, s55
	s_lshl_b32 s25, s25, 8
	s_bfe_u32 s55, s24, 0x30003
	s_lshl_b32 s55, s55, 8
	s_lshl_b32 s57, s25, 12
	s_add_u32 s62, s10, s57
	s_addc_u32 s63, s11, 0
	s_or_b32 s57, s25, 0x80
	s_lshl_b32 s57, s57, 12
	s_add_u32 s64, s10, s57
	s_addc_u32 s65, s11, 0
	s_lshl_b32 s57, s55, 12
	s_add_u32 s58, s3, s57
	s_addc_u32 s59, s51, 0
	s_or_b32 s57, s55, 0x80
	s_lshl_b32 s57, s57, 12
	s_add_u32 s60, s3, s57
	s_addc_u32 s61, s51, 0
	s_add_u32 m0, s81, 0x10000
	s_nop 0
	global_load_lds_dwordx4 v250, s[62:63]
	s_add_u32 m0, s81, 0x12000
	s_nop 0
	global_load_lds_dwordx4 v251, s[62:63]
	s_add_u32 m0, s81, 0x0
	s_nop 0
	global_load_lds_dwordx4 v250, s[58:59]
	s_add_u32 m0, s81, 0x2000
	s_nop 0
	global_load_lds_dwordx4 v251, s[58:59]
	s_add_u32 m0, s81, 0x14000
	s_nop 0
	global_load_lds_dwordx4 v250, s[64:65]
	s_add_u32 m0, s81, 0x16000
	s_nop 0
	global_load_lds_dwordx4 v251, s[64:65]
	s_add_u32 m0, s81, 0x4000
	s_nop 0
	global_load_lds_dwordx4 v250, s[60:61]
	s_add_u32 m0, s81, 0x6000
	s_nop 0
	global_load_lds_dwordx4 v251, s[60:61]
	s_mov_b32 s100, 1
.Lp6n_done:
	v_and_b32_e32 v128, 15, v142
	v_lshrrev_b32_e32 v130, 1, v142
	v_and_or_b32 v128, v130, s80, v128
	v_bfe_u32 v131, v142, 4, 2
	v_and_b32_e32 v133, 64, v140
	v_add_u32_e32 v132, s54, v128
	v_ashrrev_i32_e32 v128, 2, v142
	ds_read2st64_b32 v[142:143], v139 offset0:128 offset1:136
	v_and_b32_e32 v128, 0xffffffc0, v128
	v_lshl_or_b32 v128, v131, 2, v128
	v_add_u32_e32 v130, s52, v128
	v_xor_b32_e32 v128, 16, v140
	v_add_u32_e32 v133, 64, v133
	v_cmp_lt_i32_e32 vcc, v128, v133
	s_waitcnt lgkmcnt(0)
	v_cvt_f32_ubyte1_e32 v145, v142
	v_cvt_f32_ubyte0_e32 v144, v142
	v_cndmask_b32_e32 v128, v140, v128, vcc
	v_lshlrev_b32_e32 v136, 2, v128
	v_xor_b32_e32 v128, 32, v140
	v_pk_mul_f32 v[144:145], v[144:145], s[50:51] op_sel_hi:[1,0]
	v_cmp_lt_i32_e32 vcc, v128, v133
	v_ashrrev_i32_e32 v133, 31, v132
	v_pk_mul_f32 v[124:125], v[124:125], v[144:145]
	v_cvt_f32_ubyte3_e32 v145, v142
	v_cvt_f32_ubyte2_e32 v144, v142
	v_lshlrev_b64 v[134:135], 12, v[132:133]
	v_pk_mul_f32 v[144:145], v[144:145], s[50:51] op_sel_hi:[1,0]
	v_cndmask_b32_e32 v128, v140, v128, vcc
	v_cmp_eq_u32_e32 vcc, 0, v131
	v_lshl_add_u64 v[134:135], s[12:13], 0, v[134:135]
	v_ashrrev_i32_e32 v131, 31, v130
	v_pk_mul_f32 v[126:127], v[126:127], v[144:145]
	v_pk_mul_f32 v[144:145], v[124:125], v[124:125]
	v_pk_mul_f32 v[146:147], v[126:127], v[126:127]
	v_cvt_pk_bf16_f32 v124, v124, v125
	v_cvt_pk_bf16_f32 v125, v126, v127
	v_lshl_add_u64 v[126:127], v[130:131], 1, v[134:135]
	global_store_dwordx2 v[126:127], v[124:125], off
	v_cvt_f32_ubyte1_e32 v127, v143
	v_cvt_f32_ubyte0_e32 v126, v143
	v_pk_mul_f32 v[126:127], v[126:127], s[50:51] op_sel_hi:[1,0]
	v_add_u32_e32 v124, 16, v130
	v_pk_mul_f32 v[120:121], v[120:121], v[126:127]
	v_cvt_f32_ubyte3_e32 v127, v143
	v_cvt_f32_ubyte2_e32 v126, v143
	v_pk_mul_f32 v[126:127], v[126:127], s[50:51] op_sel_hi:[1,0]
	v_ashrrev_i32_e32 v125, 31, v124
	v_pk_mul_f32 v[122:123], v[122:123], v[126:127]
	v_pk_mul_f32 v[126:127], v[120:121], v[120:121]
	v_pk_mul_f32 v[142:143], v[122:123], v[122:123]
	v_cvt_pk_bf16_f32 v120, v120, v121
	v_cvt_pk_bf16_f32 v121, v122, v123
	ds_read2st64_b32 v[122:123], v139 offset0:144 offset1:152
	v_lshl_add_u64 v[148:149], v[124:125], 1, v[134:135]
	global_store_dwordx2 v[148:149], v[120:121], off
	v_add_u32_e32 v120, 32, v130
	v_ashrrev_i32_e32 v121, 31, v120
	s_waitcnt lgkmcnt(0)
	v_cvt_f32_ubyte1_e32 v149, v122
	v_cvt_f32_ubyte0_e32 v148, v122
	v_pk_mul_f32 v[148:149], v[148:149], s[50:51] op_sel_hi:[1,0]
	v_add_f32_e32 v126, v126, v127
	v_pk_mul_f32 v[116:117], v[116:117], v[148:149]
	v_cvt_f32_ubyte3_e32 v149, v122
	v_cvt_f32_ubyte2_e32 v148, v122
	v_pk_mul_f32 v[148:149], v[148:149], s[50:51] op_sel_hi:[1,0]
	v_add_f32_e32 v127, v144, v145
	v_pk_mul_f32 v[118:119], v[118:119], v[148:149]
	v_pk_mul_f32 v[148:149], v[116:117], v[116:117]
	v_pk_mul_f32 v[150:151], v[118:119], v[118:119]
	v_cvt_pk_bf16_f32 v116, v116, v117
	v_cvt_pk_bf16_f32 v117, v118, v119
	v_lshl_add_u64 v[118:119], v[120:121], 1, v[134:135]
	global_store_dwordx2 v[118:119], v[116:117], off
	v_cvt_f32_ubyte1_e32 v119, v123
	v_cvt_f32_ubyte0_e32 v118, v123
	v_pk_mul_f32 v[118:119], v[118:119], s[50:51] op_sel_hi:[1,0]
	v_add_u32_e32 v116, 48, v130
	v_pk_mul_f32 v[112:113], v[112:113], v[118:119]
	v_cvt_f32_ubyte3_e32 v119, v123
	v_cvt_f32_ubyte2_e32 v118, v123
	v_pk_mul_f32 v[118:119], v[118:119], s[50:51] op_sel_hi:[1,0]
	v_ashrrev_i32_e32 v117, 31, v116
	v_pk_mul_f32 v[114:115], v[114:115], v[118:119]
	v_pk_mul_f32 v[118:119], v[112:113], v[112:113]
	v_pk_mul_f32 v[122:123], v[114:115], v[114:115]
	v_cvt_pk_bf16_f32 v112, v112, v113
	v_cvt_pk_bf16_f32 v113, v114, v115
	ds_read2st64_b32 v[114:115], v139 offset0:160 offset1:168
	v_lshl_add_u64 v[152:153], v[116:117], 1, v[134:135]
	global_store_dwordx2 v[152:153], v[112:113], off
	v_add_u32_e32 v112, 0x80, v130
	v_ashrrev_i32_e32 v113, 31, v112
	s_waitcnt lgkmcnt(0)
; __device__ __forceinline__ float u8f(unsigned w, int i) { return (float)((w >> (8 * i)) & 0xffu) * (1.f / 255.f); }
; #define EPI_BEGIN_S int fo_e = fo, to_e = to; asm volatile("" : "+s"(fo_e), "+s"(to_e));
; __device__ __forceinline__ void tok_ss_atomic(float part, float* dst, int fq) {
;   part += __shfl_xor(part, 16);
;   part += __shfl_xor(part, 32);
;   if (fq == 0) atomicAdd(dst, part);
; }
; __device__ void phase6(const Params& p) {
;     ...
;     { EPI_BEGIN_S
;       const unsigned* park0 = reinterpret_cast<const unsigned*>(g_smem + 32768) + tid_e;
;       const unsigned* park1 = reinterpret_cast<const unsigned*>(g_smem + 98304) + tid_e;
;       #pragma unroll
;       for (int bj = 0; bj < 2; ++bj)
;         #pragma unroll
;         for (int n = 0; n < 2; ++n) {
;           const int t = EPI_T(bj, n);
;           const size_t rowo = (size_t)t * D;
;           float part = 0.f;
;           #pragma unroll
;           for (int ai = 0; ai < 2; ++ai)
;             #pragma unroll
;             for (int m = 0; m < 4; ++m) {
;               const size_t gi = rowo + EPI_F(ai, m);
;               const int i = ((bj * 2 + n) * 2 + ai) * 4 + m;
;               const unsigned g = (i < 16) ? park0[i * 512] : park1[(i - 16) * 512];
;               const float v0 = acc[ai][bj][m][n][0] * u8f(g, 0), v1 = acc[ai][bj][m][n][1] * u8f(g, 1);
;               const float v2 = acc[ai][bj][m][n][2] * u8f(g, 2), v3 = acc[ai][bj][m][n][3] * u8f(g, 3);
;               part += v0 * v0 + v1 * v1 + v2 * v2 + v3 * v3;
;               v2u ov; ov.x = pk2(v0, v1); ov.y = pk2(v2, v3);
;               *reinterpret_cast<v2u*>(e + gi) = ov;
;             }
;           tok_ss_atomic(part, sse + t, fq);
	v_cvt_f32_ubyte1_e32 v153, v114
	v_cvt_f32_ubyte0_e32 v152, v114
	v_pk_mul_f32 v[152:153], v[152:153], s[50:51] op_sel_hi:[1,0]
	v_add_f32_e32 v126, v142, v126
	v_pk_mul_f32 v[108:109], v[108:109], v[152:153]
	v_cvt_f32_ubyte3_e32 v153, v114
	v_cvt_f32_ubyte2_e32 v152, v114
	v_pk_mul_f32 v[152:153], v[152:153], s[50:51] op_sel_hi:[1,0]
	v_add_f32_e32 v127, v146, v127
	v_pk_mul_f32 v[110:111], v[110:111], v[152:153]
	v_pk_mul_f32 v[152:153], v[108:109], v[108:109]
	v_pk_mul_f32 v[154:155], v[110:111], v[110:111]
	v_cvt_pk_bf16_f32 v108, v108, v109
	v_cvt_pk_bf16_f32 v109, v110, v111
	v_lshl_add_u64 v[110:111], v[112:113], 1, v[134:135]
	global_store_dwordx2 v[110:111], v[108:109], off
	v_cvt_f32_ubyte1_e32 v111, v115
	v_cvt_f32_ubyte0_e32 v110, v115
	v_pk_mul_f32 v[110:111], v[110:111], s[50:51] op_sel_hi:[1,0]
	v_add_u32_e32 v108, 0x90, v130
	v_pk_mul_f32 v[104:105], v[104:105], v[110:111]
	v_cvt_f32_ubyte3_e32 v111, v115
	v_cvt_f32_ubyte2_e32 v110, v115
	v_pk_mul_f32 v[110:111], v[110:111], s[50:51] op_sel_hi:[1,0]
	v_ashrrev_i32_e32 v109, 31, v108
	v_pk_mul_f32 v[106:107], v[106:107], v[110:111]
	v_pk_mul_f32 v[110:111], v[104:105], v[104:105]
	v_pk_mul_f32 v[114:115], v[106:107], v[106:107]
	v_cvt_pk_bf16_f32 v104, v104, v105
	v_cvt_pk_bf16_f32 v105, v106, v107
	ds_read2st64_b32 v[106:107], v139 offset0:176 offset1:184
	v_lshl_add_u64 v[156:157], v[108:109], 1, v[134:135]
	global_store_dwordx2 v[156:157], v[104:105], off
	v_add_f32_e32 v126, v143, v126
	v_add_f32_e32 v127, v147, v127
	s_waitcnt lgkmcnt(0)
	v_cvt_f32_ubyte1_e32 v157, v106
	v_cvt_f32_ubyte0_e32 v156, v106
	v_pk_mul_f32 v[156:157], v[156:157], s[50:51] op_sel_hi:[1,0]
	v_add_f32_e32 v126, v127, v126
	v_pk_mul_f32 v[100:101], v[100:101], v[156:157]
	v_cvt_f32_ubyte3_e32 v157, v106
	v_cvt_f32_ubyte2_e32 v156, v106
	v_pk_mul_f32 v[156:157], v[156:157], s[50:51] op_sel_hi:[1,0]
	v_add_f32_e32 v127, v148, v149
	v_pk_mul_f32 v[102:103], v[102:103], v[156:157]
	v_pk_mul_f32 v[156:157], v[100:101], v[100:101]
	v_pk_mul_f32 v[158:159], v[102:103], v[102:103]
	v_cvt_pk_bf16_f32 v100, v100, v101
	v_cvt_pk_bf16_f32 v101, v102, v103
	v_cvt_f32_ubyte1_e32 v103, v107
	v_cvt_f32_ubyte0_e32 v102, v107
	v_pk_mul_f32 v[102:103], v[102:103], s[50:51] op_sel_hi:[1,0]
	v_add_f32_e32 v127, v150, v127
	v_add_f32_e32 v118, v118, v119
	v_pk_mul_f32 v[102:103], v[96:97], v[102:103]
	v_cvt_f32_ubyte3_e32 v97, v107
	v_cvt_f32_ubyte2_e32 v96, v107
	v_add_f32_e32 v127, v151, v127
	v_add_f32_e32 v118, v122, v118
	v_add_f32_e32 v119, v152, v153
	v_pk_mul_f32 v[96:97], v[96:97], s[50:51] op_sel_hi:[1,0]
	v_add_f32_e32 v126, v126, v127
	v_add_f32_e32 v118, v123, v118
	v_add_f32_e32 v119, v154, v119
	v_add_f32_e32 v110, v110, v111
	v_pk_mul_f32 v[106:107], v[98:99], v[96:97]
	v_pk_mul_f32 v[96:97], v[102:103], v[102:103]
	v_add_f32_e32 v118, v126, v118
	v_add_f32_e32 v119, v155, v119
	v_add_f32_e32 v110, v114, v110
	v_add_f32_e32 v111, v156, v157
	v_pk_mul_f32 v[98:99], v[106:107], v[106:107]
	v_add_f32_e32 v118, v118, v119
	v_add_f32_e32 v110, v115, v110
	v_add_f32_e32 v111, v158, v111
	v_add_f32_e32 v96, v96, v97
	v_add_f32_e32 v110, v118, v110
	v_add_f32_e32 v111, v159, v111
	v_add_f32_e32 v96, v98, v96
	v_add_f32_e32 v110, v110, v111
	v_add_f32_e32 v96, v99, v96
	v_add_f32_e32 v98, v110, v96
	ds_bpermute_b32 v99, v136, v98
	v_lshlrev_b32_e32 v128, 2, v128
	v_add_u32_e32 v104, 0xa0, v130
	v_ashrrev_i32_e32 v105, 31, v104
	v_lshl_add_u64 v[96:97], v[104:105], 1, v[134:135]
	s_waitcnt lgkmcnt(0)
	v_add_f32_e32 v98, v98, v99
	ds_bpermute_b32 v99, v128, v98
	global_store_dwordx2 v[96:97], v[100:101], off
	v_add_u32_e32 v96, 0xb0, v130
	v_ashrrev_i32_e32 v97, 31, v96
	v_cvt_pk_bf16_f32 v100, v102, v103
	v_cvt_pk_bf16_f32 v101, v106, v107
	v_lshl_add_u64 v[102:103], v[96:97], 1, v[134:135]
	global_store_dwordx2 v[102:103], v[100:101], off
	s_and_saveexec_b64 s[52:53], vcc
	s_cbranch_execz .LBB0_778
	v_lshl_add_u64 v[100:101], v[132:133], 2, s[6:7]
	s_waitcnt lgkmcnt(0)
	v_add_f32_e32 v98, v98, v99
	global_atomic_add_f32 v[100:101], v98, off
